# A-panel warm-up: in the four store-bound epilogues before an XCD switches to its second row-panel group (P1, P4, P9) each wave touches 8 KiB of the next 8 MB A panel with dummy loads
# baseline (speedup 1.0000x reference)
; #define PG8_LAS __attribute__((address_space(3)))
; #define PG8_STAGE(bufoff, gbase, voff) do { _Pragma("unroll") for (int _i = 0; _i < 2; ++_i) \
;         __builtin_amdgcn_global_load_lds((const unsigned*)((const char*)(gbase) + (voff)[_i]), (PG8_LAS unsigned*)(lds + (bufoff) + ldsw + _i * 8192), 16, 0, 0); } while (0)
; #define PG8_WAIT_V(n) asm volatile("s_waitcnt vmcnt(" #n ")" ::: "memory")
; #define PG8_BAR __builtin_amdgcn_s_barrier()
; template <class Epi, class Sched, bool ALIGN_EPI = false, bool SP2 = false>
; __device__ __forceinline__ void gemm_phase(PG8_LAS unsigned char* lds, const Gemm g, const Sched& S, const Epi& E, int tid_in) {
;     ...
;         PG8_WAIT_V(2); PG8_BAR;
;         PG8_STAGE(PG8_SB(1, 0), cB + kstep, voffB); PG8_STAGE(PG8_SA(1, 0), cA + kstep, voffA); PG8_STAGE(PG8_SB(1, 1), cB + hstepB + kstep, voffB);
;         PG8_WAIT_V(6); PG8_BAR;
;     __device__ __forceinline__ void operator()(const f32x4 (&acc)[2][2][4][2], const Unit& u, int wr, int wc, int fr, int fq) const {
;         const int lane = fr + 16 * fq; PG8_LAS unsigned char* stg = lds + STG_OFF + (wr * 4 + wc) * STG_WAVE;
;         const PG8_LAS float* rtab = (const PG8_LAS float*)(lds + RSTD_OFF) + ((u.pm >> 3) & 3) * 256;
.LBB0_74:
	s_mov_b64 s[10:11], 0x80
	s_and_b32 s33, s7, 3
	s_add_i32 m0, s47, 0x18000
	v_lshl_add_u64 v[6:7], v[6:7], 0, s[10:11]
	s_lshl_b32 s60, s38, 6
	s_lshl_b32 s15, s38, 13
	s_lshl_b32 s39, s33, 12
	s_waitcnt vmcnt(2)
	s_barrier
	global_load_lds_dwordx4 v[6:7], off
	v_lshl_add_u64 v[4:5], v[4:5], 0, s[10:11]
	s_add_i32 m0, s47, 0x1a000
	s_add_i32 s61, s47, 0x8000
	s_add_i32 s62, s47, 0xa000
	global_load_lds_dwordx4 v[4:5], off
	v_lshl_add_u64 v[0:1], v[0:1], 0, s[10:11]
	s_mov_b32 m0, s61
	s_add_u32 s26, s50, 0x20080
	global_load_lds_dwordx4 v[0:1], off
	v_lshl_add_u64 v[0:1], v[2:3], 0, s[10:11]
	s_mov_b32 m0, s62
	s_addc_u32 s27, s51, 0
	global_load_lds_dwordx4 v[0:1], off
	s_add_i32 m0, s47, 0x1c000
	v_lshl_add_u64 v[0:1], s[26:27], 0, v[132:133]
	global_load_lds_dwordx4 v[0:1], off
	v_lshl_add_u64 v[0:1], s[26:27], 0, v[128:129]
	s_add_i32 m0, s47, 0x1e000
	v_and_b32_e32 v2, 48, v10
	global_load_lds_dwordx4 v[0:1], off
	v_and_b32_e32 v0, 15, v10
	v_lshlrev_b32_e32 v3, 2, v0
	v_lshl_or_b32 v1, v0, 6, v2
	v_and_b32_e32 v4, 32, v3
	s_cmpk_lt_u32 s14, 0x100
	s_sext_i32_i16 s69, s6
	v_bitop3_b32 v5, v1, s15, v4 bitop3:0xde
	s_cselect_b64 s[14:15], -1, 0
	s_lshl_b32 s6, s38, 2
	s_or_b32 s6, s6, s33
	s_mulk_i32 s6, 0x900
	s_lshl_b32 s26, s38, 8
	s_add_i32 s6, s6, 0
	s_add_i32 s26, s26, 0
	s_add_i32 s6, s6, 0x20000
	s_add_i32 s26, s26, 0x24800
	v_bitop3_b32 v146, v1, s39, v4 bitop3:0xde
	v_add_u32_e32 v147, s26, v3
	s_movk_i32 s26, 0x90
	v_mov_b32_e32 v1, s6
	v_mad_u32_u24 v3, v0, s26, v1
	v_and_b32_e32 v0, 0x70, v12
	v_add_u32_e32 v4, s6, v0
	s_lshl_b32 s6, s7, 7
	s_bfe_u32 s63, s7, 0x10001
	s_and_b32 s6, s6, 0x80
	s_add_u32 s6, s34, s6
	s_addc_u32 s7, s35, 0
	v_mov_b32_e32 v1, v133
	v_lshl_add_u64 v[136:137], s[6:7], 0, v[0:1]
	v_lshlrev_b32_e32 v0, 15, v14
	v_and_b32_e32 v0, 0xffff0000, v0
	v_lshl_add_u32 v0, v13, 12, v0
	v_and_b32_e32 v1, 1, v14
	v_lshl_or_b32 v0, v1, 6, v0
	v_lshl_add_u32 v138, v15, 1, v0
	v_lshlrev_b32_e32 v0, 15, v8
	v_and_b32_e32 v0, 0xffff0000, v0
	s_waitcnt vmcnt(6)
	v_bfe_u32 v148, v10, 3, 3
	v_lshl_add_u32 v0, v9, 12, v0
	v_and_b32_e32 v1, 1, v8
	v_mul_u32_u24_e32 v6, 0x90, v148
	v_lshl_or_b32 v0, v1, 6, v0
	s_add_i32 s67, 0, 0x10000
	s_add_i32 s68, 0, 0x14000
	v_or_b32_e32 v149, 8, v148
	s_or_b32 s64, s60, 16
	s_or_b32 s65, s60, 32
	s_or_b32 s66, s60, 48
	v_mov_b32_e32 v139, v133
	v_lshl_add_u32 v140, v11, 1, v0
	v_mov_b32_e32 v141, v133
	v_mov_b64_e32 v[142:143], 0xc00
	v_mov_b64_e32 v[144:145], 0xbff
	v_add_u32_e32 v150, s67, v146
	v_add_u32_e32 v151, s68, v146
	v_add_u32_e32 v152, 0, v5
	v_add_u32_e32 v153, v3, v2
	v_add_u32_e32 v154, v4, v6
	s_barrier
	s_waitcnt vmcnt(0)
	s_mov_b32 s99, 0
	s_branch .LBB0_77

; #define PG8_STAGE(bufoff, gbase, voff) do { _Pragma("unroll") for (int _i = 0; _i < 2; ++_i) \
;         __builtin_amdgcn_global_load_lds((const unsigned*)((const char*)(gbase) + (voff)[_i]), (PG8_LAS unsigned*)(lds + (bufoff) + ldsw + _i * 8192), 16, 0, 0); } while (0)
; #define PG8_LDA(dst, b, h) do { _Pragma("unroll") for (int m = 0; m < 4; ++m) _Pragma("unroll") for (int k = 0; k < 2; ++k) dst[m][k] = *(const PG8_LAS bf16x8*)(lds + PG8_SA(b, h) + aoff + m * 2048 + k * 1024); } while (0)
; #define PG8_LDB(dst, b, h) do { _Pragma("unroll") for (int n = 0; n < 2; ++n) _Pragma("unroll") for (int k = 0; k < 2; ++k) dst[n][k] = *(const PG8_LAS bf16x8*)(lds + PG8_SB(b, h) + boff + n * 2048 + k * 1024); } while (0)
; #define PG8_MMA(ai, bj, At, Bt) do { __builtin_amdgcn_s_setprio(1); _Pragma("unroll") for (int m = 0; m < 4; ++m) _Pragma("unroll") for (int n = 0; n < 2; ++n) _Pragma("unroll") for (int k = 0; k < 2; ++k) \
;         acc[ai][bj][m][n] = __builtin_amdgcn_mfma_f32_16x16x32_bf16(Bt[n][k], At[m][k], acc[ai][bj][m][n], 0, 0, 0); __builtin_amdgcn_s_setprio(0); } while (0)
; #define PG8_WAIT_V(n) asm volatile("s_waitcnt vmcnt(" #n ")" ::: "memory")
; #define PG8_WAIT_L(n) asm volatile("s_waitcnt lgkmcnt(" #n ")" ::: "memory")
; #define PG8_BAR __builtin_amdgcn_s_barrier()
; #define PG8_SCHED __builtin_amdgcn_sched_barrier(0)
; template <class Epi, class Sched, bool ALIGN_EPI = false, bool SP2 = false>
; __device__ __forceinline__ void gemm_phase(PG8_LAS unsigned char* lds, const Gemm g, const Sched& S, const Epi& E, int tid_in) {
;     ...
;             PG8_LDB(B0, 0, 0); PG8_LDB(B1, 0, 1); PG8_SCHED; PG8_LDA(At, 0, 0); PG8_STAGE(PG8_SA(1, 1), a1 + hstep, voffA);
;             PG8_WAIT_V(8); PG8_WAIT_L(0); PG8_BAR; PG8_MMA(0, 0, At, B0); PG8_MMA(0, 1, At, B1); PG8_BAR; PG8_SCHED;
;             PG8_LDA(At, 0, 1); PG8_STAGE(PG8_SB(0, 0), b2, voffB); PG8_STAGE(PG8_SB(0, 1), b2 + hstepB, voffB); PG8_STAGE(PG8_SA(0, 0), a2, voffA);
;             PG8_WAIT_V(8); PG8_WAIT_L(0); PG8_BAR; PG8_MMA(1, 0, At, B0); PG8_MMA(1, 1, At, B1); PG8_BAR; PG8_SCHED;
.Lkb_skip_0:
.LBB0_80:
	ds_read_b128 v[156:159], v150
	ds_read_b128 v[160:163], v150 offset:1024
	ds_read_b128 v[164:167], v150 offset:2048
	ds_read_b128 v[168:171], v150 offset:3072
	ds_read_b128 v[172:175], v151
	ds_read_b128 v[176:179], v151 offset:1024
	ds_read_b128 v[180:183], v151 offset:2048
	ds_read_b128 v[184:187], v151 offset:3072
	s_add_u32 s26, s48, 0xfff80080
	s_addc_u32 s27, s49, -1
	s_cmp_eq_u32 s76, 28
	s_cselect_b32 s53, s41, s27
	s_cselect_b32 s52, s70, s26
	s_cselect_b32 s51, s39, s75
	s_cselect_b32 s50, s71, s74
	v_lshl_add_u64 v[204:205], s[48:49], 0, v[138:139]
	s_add_i32 m0, s47, 0xc000
	ds_read_b128 v[188:191], v152
	ds_read_b128 v[192:195], v152 offset:1024
	ds_read_b128 v[196:199], v152 offset:2048
	ds_read_b128 v[200:203], v152 offset:3072
	ds_read_b128 v[212:215], v152 offset:4096
	ds_read_b128 v[216:219], v152 offset:5120
	ds_read_b128 v[220:223], v152 offset:6144
	ds_read_b128 v[224:227], v152 offset:7168
	global_load_lds_dwordx4 v[204:205], off
	v_lshl_add_u64 v[204:205], s[48:49], 0, v[140:141]
	s_add_i32 m0, s47, 0xe000
	s_nop 0
	global_load_lds_dwordx4 v[204:205], off
	s_waitcnt vmcnt(8)
	s_waitcnt lgkmcnt(0)
	s_barrier
	s_setprio 1
	s_waitcnt lgkmcnt(0)
	v_mfma_f32_16x16x32_bf16 v[124:127], v[156:159], v[188:191], v[124:127]
	v_mfma_f32_16x16x32_bf16 v[120:123], v[164:167], v[188:191], v[120:123]
	v_mfma_f32_16x16x32_bf16 v[108:111], v[156:159], v[196:199], v[108:111]
	v_mfma_f32_16x16x32_bf16 v[104:107], v[164:167], v[196:199], v[104:107]
	v_mfma_f32_16x16x32_bf16 v[92:95], v[156:159], v[212:215], v[92:95]
	v_mfma_f32_16x16x32_bf16 v[88:91], v[164:167], v[212:215], v[88:91]
	v_mfma_f32_16x16x32_bf16 v[76:79], v[156:159], v[220:223], v[76:79]
	v_mfma_f32_16x16x32_bf16 v[72:75], v[164:167], v[220:223], v[72:75]
	v_mfma_f32_16x16x32_bf16 v[124:127], v[160:163], v[192:195], v[124:127]
	v_mfma_f32_16x16x32_bf16 v[120:123], v[168:171], v[192:195], v[120:123]
	v_mfma_f32_16x16x32_bf16 v[108:111], v[160:163], v[200:203], v[108:111]
	v_mfma_f32_16x16x32_bf16 v[104:107], v[168:171], v[200:203], v[104:107]
	v_mfma_f32_16x16x32_bf16 v[92:95], v[160:163], v[216:219], v[92:95]
	v_mfma_f32_16x16x32_bf16 v[88:91], v[168:171], v[216:219], v[88:91]
	v_mfma_f32_16x16x32_bf16 v[76:79], v[160:163], v[224:227], v[76:79]
	v_mfma_f32_16x16x32_bf16 v[72:75], v[168:171], v[224:227], v[72:75]
	s_setprio 0
	s_setprio 1
	v_mfma_f32_16x16x32_bf16 v[116:119], v[172:175], v[188:191], v[116:119]
	v_mfma_f32_16x16x32_bf16 v[112:115], v[180:183], v[188:191], v[112:115]
	v_mfma_f32_16x16x32_bf16 v[100:103], v[172:175], v[196:199], v[100:103]
	v_mfma_f32_16x16x32_bf16 v[96:99], v[180:183], v[196:199], v[96:99]
	v_mfma_f32_16x16x32_bf16 v[84:87], v[172:175], v[212:215], v[84:87]
	v_mfma_f32_16x16x32_bf16 v[80:83], v[180:183], v[212:215], v[80:83]
	v_mfma_f32_16x16x32_bf16 v[68:71], v[172:175], v[220:223], v[68:71]
	v_mfma_f32_16x16x32_bf16 v[64:67], v[180:183], v[220:223], v[64:67]
	v_mfma_f32_16x16x32_bf16 v[116:119], v[176:179], v[192:195], v[116:119]
	v_mfma_f32_16x16x32_bf16 v[112:115], v[184:187], v[192:195], v[112:115]
	v_mfma_f32_16x16x32_bf16 v[100:103], v[176:179], v[200:203], v[100:103]
	v_mfma_f32_16x16x32_bf16 v[96:99], v[184:187], v[200:203], v[96:99]
	v_mfma_f32_16x16x32_bf16 v[84:87], v[176:179], v[216:219], v[84:87]
	v_mfma_f32_16x16x32_bf16 v[80:83], v[184:187], v[216:219], v[80:83]
	v_mfma_f32_16x16x32_bf16 v[68:71], v[176:179], v[224:227], v[68:71]
	v_mfma_f32_16x16x32_bf16 v[64:67], v[184:187], v[224:227], v[64:67]
	s_setprio 0
	s_barrier
	s_add_i32 s26, s67, s54
	v_lshl_add_u64 v[204:205], s[50:51], 0, v[132:133]
	s_mov_b32 m0, s26
	ds_read_b128 v[188:191], v152 offset:16384
	ds_read_b128 v[192:195], v152 offset:17408
	ds_read_b128 v[196:199], v152 offset:18432
	ds_read_b128 v[200:203], v152 offset:19456
	ds_read_b128 v[212:215], v152 offset:20480
	ds_read_b128 v[216:219], v152 offset:21504
	ds_read_b128 v[220:223], v152 offset:22528
	ds_read_b128 v[224:227], v152 offset:23552
	global_load_lds_dwordx4 v[204:205], off
	s_add_i32 m0, s26, 0x2000
	s_add_u32 s26, s50, 0x20000
	v_lshl_add_u64 v[206:207], s[50:51], 0, v[128:129]
	s_addc_u32 s27, s51, 0
	s_add_i32 s33, s68, s54
	global_load_lds_dwordx4 v[206:207], off
	v_lshl_add_u64 v[208:209], s[26:27], 0, v[132:133]
	s_mov_b32 m0, s33
	v_lshl_add_u64 v[228:229], s[52:53], 0, v[130:131]
	global_load_lds_dwordx4 v[208:209], off
	v_lshl_add_u64 v[208:209], s[26:27], 0, v[128:129]
	s_add_i32 m0, s33, 0x2000
	s_nop 0
	global_load_lds_dwordx4 v[208:209], off
	v_lshl_add_u64 v[208:209], s[52:53], 0, v[134:135]
	s_mov_b32 m0, s47
	s_nop 0
	global_load_lds_dwordx4 v[208:209], off
	s_mov_b32 m0, s56
	s_nop 0
	global_load_lds_dwordx4 v[228:229], off
	s_waitcnt vmcnt(8)
	s_waitcnt lgkmcnt(0)
	s_barrier
; #define PG8_STAGE(bufoff, gbase, voff) do { _Pragma("unroll") for (int _i = 0; _i < 2; ++_i) \
;         __builtin_amdgcn_global_load_lds((const unsigned*)((const char*)(gbase) + (voff)[_i]), (PG8_LAS unsigned*)(lds + (bufoff) + ldsw + _i * 8192), 16, 0, 0); } while (0)
; #define PG8_LDA(dst, b, h) do { _Pragma("unroll") for (int m = 0; m < 4; ++m) _Pragma("unroll") for (int k = 0; k < 2; ++k) dst[m][k] = *(const PG8_LAS bf16x8*)(lds + PG8_SA(b, h) + aoff + m * 2048 + k * 1024); } while (0)
; #define PG8_LDB(dst, b, h) do { _Pragma("unroll") for (int n = 0; n < 2; ++n) _Pragma("unroll") for (int k = 0; k < 2; ++k) dst[n][k] = *(const PG8_LAS bf16x8*)(lds + PG8_SB(b, h) + boff + n * 2048 + k * 1024); } while (0)
; #define PG8_MMA(ai, bj, At, Bt) do { __builtin_amdgcn_s_setprio(1); _Pragma("unroll") for (int m = 0; m < 4; ++m) _Pragma("unroll") for (int n = 0; n < 2; ++n) _Pragma("unroll") for (int k = 0; k < 2; ++k) \
;         acc[ai][bj][m][n] = __builtin_amdgcn_mfma_f32_16x16x32_bf16(Bt[n][k], At[m][k], acc[ai][bj][m][n], 0, 0, 0); __builtin_amdgcn_s_setprio(0); } while (0)
; #define PG8_WAIT_V(n) asm volatile("s_waitcnt vmcnt(" #n ")" ::: "memory")
; #define PG8_WAIT_L(n) asm volatile("s_waitcnt lgkmcnt(" #n ")" ::: "memory")
; #define PG8_BAR __builtin_amdgcn_s_barrier()
; #define PG8_SCHED __builtin_amdgcn_sched_barrier(0)
; template <class Epi, class Sched, bool ALIGN_EPI = false, bool SP2 = false>
; __device__ __forceinline__ void gemm_phase(PG8_LAS unsigned char* lds, const Gemm g, const Sched& S, const Epi& E, int tid_in) {
;     ...
;             PG8_WAIT_V(8); PG8_WAIT_L(0); PG8_BAR; PG8_MMA(1, 0, At, B0); PG8_MMA(1, 1, At, B1); PG8_BAR; PG8_SCHED;
;             PG8_LDB(B0, 1, 0); PG8_LDB(B1, 1, 1); PG8_SCHED; PG8_LDA(At, 1, 0); PG8_STAGE(PG8_SA(0, 1), a2 + hstep, voffA);
;             PG8_WAIT_V(8); PG8_WAIT_L(0); PG8_BAR; PG8_MMA(0, 0, At, B0); PG8_MMA(0, 1, At, B1); PG8_BAR; PG8_SCHED;
	s_setprio 1
	s_waitcnt lgkmcnt(0)
	v_mfma_f32_16x16x32_bf16 v[60:63], v[156:159], v[188:191], v[60:63]
	v_mfma_f32_16x16x32_bf16 v[56:59], v[164:167], v[188:191], v[56:59]
	v_mfma_f32_16x16x32_bf16 v[44:47], v[156:159], v[196:199], v[44:47]
	v_mfma_f32_16x16x32_bf16 v[40:43], v[164:167], v[196:199], v[40:43]
	v_mfma_f32_16x16x32_bf16 v[28:31], v[156:159], v[212:215], v[28:31]
	v_mfma_f32_16x16x32_bf16 v[24:27], v[164:167], v[212:215], v[24:27]
	v_mfma_f32_16x16x32_bf16 v[12:15], v[156:159], v[220:223], v[12:15]
	v_mfma_f32_16x16x32_bf16 v[8:11], v[164:167], v[220:223], v[8:11]
	v_mfma_f32_16x16x32_bf16 v[60:63], v[160:163], v[192:195], v[60:63]
	v_mfma_f32_16x16x32_bf16 v[56:59], v[168:171], v[192:195], v[56:59]
	v_mfma_f32_16x16x32_bf16 v[44:47], v[160:163], v[200:203], v[44:47]
	v_mfma_f32_16x16x32_bf16 v[40:43], v[168:171], v[200:203], v[40:43]
	v_mfma_f32_16x16x32_bf16 v[28:31], v[160:163], v[216:219], v[28:31]
	v_mfma_f32_16x16x32_bf16 v[24:27], v[168:171], v[216:219], v[24:27]
	v_mfma_f32_16x16x32_bf16 v[12:15], v[160:163], v[224:227], v[12:15]
	v_mfma_f32_16x16x32_bf16 v[8:11], v[168:171], v[224:227], v[8:11]
	s_setprio 0
	s_setprio 1
	v_mfma_f32_16x16x32_bf16 v[52:55], v[172:175], v[188:191], v[52:55]
	v_mfma_f32_16x16x32_bf16 v[48:51], v[180:183], v[188:191], v[48:51]
	v_mfma_f32_16x16x32_bf16 v[36:39], v[172:175], v[196:199], v[36:39]
	v_mfma_f32_16x16x32_bf16 v[32:35], v[180:183], v[196:199], v[32:35]
	v_mfma_f32_16x16x32_bf16 v[20:23], v[172:175], v[212:215], v[20:23]
	v_mfma_f32_16x16x32_bf16 v[16:19], v[180:183], v[212:215], v[16:19]
	v_mfma_f32_16x16x32_bf16 v[4:7], v[172:175], v[220:223], v[4:7]
	v_mfma_f32_16x16x32_bf16 v[0:3], v[180:183], v[220:223], v[0:3]
	v_mfma_f32_16x16x32_bf16 v[52:55], v[176:179], v[192:195], v[52:55]
	v_mfma_f32_16x16x32_bf16 v[48:51], v[184:187], v[192:195], v[48:51]
	v_mfma_f32_16x16x32_bf16 v[36:39], v[176:179], v[200:203], v[36:39]
	v_mfma_f32_16x16x32_bf16 v[32:35], v[184:187], v[200:203], v[32:35]
	v_mfma_f32_16x16x32_bf16 v[20:23], v[176:179], v[216:219], v[20:23]
	v_mfma_f32_16x16x32_bf16 v[16:19], v[184:187], v[216:219], v[16:19]
	v_mfma_f32_16x16x32_bf16 v[4:7], v[176:179], v[224:227], v[4:7]
	v_mfma_f32_16x16x32_bf16 v[0:3], v[184:187], v[224:227], v[0:3]
	s_setprio 0
	s_barrier
	s_add_i32 s33, 0, 0x18000
	v_add_u32_e32 v155, s33, v146
	s_add_i32 s77, 0, 0x1c000
	ds_read_b128 v[156:159], v155
	ds_read_b128 v[160:163], v155 offset:1024
	ds_read_b128 v[164:167], v155 offset:2048
	ds_read_b128 v[168:171], v155 offset:3072
	v_add_u32_e32 v155, s77, v146
	ds_read_b128 v[172:175], v155
	ds_read_b128 v[176:179], v155 offset:1024
	ds_read_b128 v[180:183], v155 offset:2048
	ds_read_b128 v[184:187], v155 offset:3072
	s_add_u32 s26, s52, 0x80000
	s_addc_u32 s27, s53, 0
	s_mov_b32 m0, s57
	v_lshl_add_u64 v[230:231], s[26:27], 0, v[134:135]
	ds_read_b128 v[188:191], v152 offset:32768
	ds_read_b128 v[192:195], v152 offset:33792
	ds_read_b128 v[196:199], v152 offset:34816
	ds_read_b128 v[200:203], v152 offset:35840
	ds_read_b128 v[212:215], v152 offset:36864
	ds_read_b128 v[216:219], v152 offset:37888
	ds_read_b128 v[220:223], v152 offset:38912
	ds_read_b128 v[224:227], v152 offset:39936
	global_load_lds_dwordx4 v[230:231], off
	v_lshl_add_u64 v[230:231], s[26:27], 0, v[130:131]
	s_mov_b32 m0, s58
	s_nop 0
	global_load_lds_dwordx4 v[230:231], off
	s_waitcnt vmcnt(8)
	s_waitcnt lgkmcnt(0)
	s_barrier
	s_setprio 1
	s_waitcnt lgkmcnt(0)
	v_mfma_f32_16x16x32_bf16 v[124:127], v[156:159], v[188:191], v[124:127]
	v_mfma_f32_16x16x32_bf16 v[120:123], v[164:167], v[188:191], v[120:123]
	v_mfma_f32_16x16x32_bf16 v[108:111], v[156:159], v[196:199], v[108:111]
	v_mfma_f32_16x16x32_bf16 v[104:107], v[164:167], v[196:199], v[104:107]
	v_mfma_f32_16x16x32_bf16 v[92:95], v[156:159], v[212:215], v[92:95]
	v_mfma_f32_16x16x32_bf16 v[88:91], v[164:167], v[212:215], v[88:91]
	v_mfma_f32_16x16x32_bf16 v[76:79], v[156:159], v[220:223], v[76:79]
	v_mfma_f32_16x16x32_bf16 v[72:75], v[164:167], v[220:223], v[72:75]
	v_mfma_f32_16x16x32_bf16 v[124:127], v[160:163], v[192:195], v[124:127]
	v_mfma_f32_16x16x32_bf16 v[120:123], v[168:171], v[192:195], v[120:123]
	v_mfma_f32_16x16x32_bf16 v[108:111], v[160:163], v[200:203], v[108:111]
	v_mfma_f32_16x16x32_bf16 v[104:107], v[168:171], v[200:203], v[104:107]
	v_mfma_f32_16x16x32_bf16 v[92:95], v[160:163], v[216:219], v[92:95]
	v_mfma_f32_16x16x32_bf16 v[88:91], v[168:171], v[216:219], v[88:91]
	v_mfma_f32_16x16x32_bf16 v[76:79], v[160:163], v[224:227], v[76:79]
	v_mfma_f32_16x16x32_bf16 v[72:75], v[168:171], v[224:227], v[72:75]
	s_setprio 0
	s_setprio 1
	v_mfma_f32_16x16x32_bf16 v[116:119], v[172:175], v[188:191], v[116:119]
	v_mfma_f32_16x16x32_bf16 v[112:115], v[180:183], v[188:191], v[112:115]
	v_mfma_f32_16x16x32_bf16 v[100:103], v[172:175], v[196:199], v[100:103]
	v_mfma_f32_16x16x32_bf16 v[96:99], v[180:183], v[196:199], v[96:99]
	v_mfma_f32_16x16x32_bf16 v[84:87], v[172:175], v[212:215], v[84:87]
	v_mfma_f32_16x16x32_bf16 v[80:83], v[180:183], v[212:215], v[80:83]
	v_mfma_f32_16x16x32_bf16 v[68:71], v[172:175], v[220:223], v[68:71]
	v_mfma_f32_16x16x32_bf16 v[64:67], v[180:183], v[220:223], v[64:67]
	v_mfma_f32_16x16x32_bf16 v[116:119], v[176:179], v[192:195], v[116:119]
	v_mfma_f32_16x16x32_bf16 v[112:115], v[184:187], v[192:195], v[112:115]
	v_mfma_f32_16x16x32_bf16 v[100:103], v[176:179], v[200:203], v[100:103]
	v_mfma_f32_16x16x32_bf16 v[96:99], v[184:187], v[200:203], v[96:99]
	v_mfma_f32_16x16x32_bf16 v[84:87], v[176:179], v[216:219], v[84:87]
	v_mfma_f32_16x16x32_bf16 v[80:83], v[184:187], v[216:219], v[80:83]
	v_mfma_f32_16x16x32_bf16 v[68:71], v[176:179], v[224:227], v[68:71]
	v_mfma_f32_16x16x32_bf16 v[64:67], v[184:187], v[224:227], v[64:67]
	s_setprio 0
	s_barrier
; #define PG8_STAGE(bufoff, gbase, voff) do { _Pragma("unroll") for (int _i = 0; _i < 2; ++_i) \
;         __builtin_amdgcn_global_load_lds((const unsigned*)((const char*)(gbase) + (voff)[_i]), (PG8_LAS unsigned*)(lds + (bufoff) + ldsw + _i * 8192), 16, 0, 0); } while (0)
; #define PG8_LDA(dst, b, h) do { _Pragma("unroll") for (int m = 0; m < 4; ++m) _Pragma("unroll") for (int k = 0; k < 2; ++k) dst[m][k] = *(const PG8_LAS bf16x8*)(lds + PG8_SA(b, h) + aoff + m * 2048 + k * 1024); } while (0)
; #define PG8_MMA(ai, bj, At, Bt) do { __builtin_amdgcn_s_setprio(1); _Pragma("unroll") for (int m = 0; m < 4; ++m) _Pragma("unroll") for (int n = 0; n < 2; ++n) _Pragma("unroll") for (int k = 0; k < 2; ++k) \
;         acc[ai][bj][m][n] = __builtin_amdgcn_mfma_f32_16x16x32_bf16(Bt[n][k], At[m][k], acc[ai][bj][m][n], 0, 0, 0); __builtin_amdgcn_s_setprio(0); } while (0)
; #define PG8_WAIT_V(n) asm volatile("s_waitcnt vmcnt(" #n ")" ::: "memory")
; #define PG8_WAIT_L(n) asm volatile("s_waitcnt lgkmcnt(" #n ")" ::: "memory")
; #define PG8_BAR __builtin_amdgcn_s_barrier()
; #define PG8_SCHED __builtin_amdgcn_sched_barrier(0)
; template <class Epi, class Sched, bool ALIGN_EPI = false, bool SP2 = false>
; __device__ __forceinline__ void gemm_phase(PG8_LAS unsigned char* lds, const Gemm g, const Sched& S, const Epi& E, int tid_in) {
;     ...
;             PG8_WAIT_V(8); PG8_WAIT_L(0); PG8_BAR; PG8_MMA(0, 0, At, B0); PG8_MMA(0, 1, At, B1); PG8_BAR; PG8_SCHED;
;             PG8_LDA(At, 1, 1); PG8_STAGE(PG8_SB(1, 0), b3, voffB); PG8_STAGE(PG8_SB(1, 1), b3 + hstepB, voffB); PG8_STAGE(PG8_SA(1, 0), a3, voffA);
;             PG8_WAIT_V(8); PG8_WAIT_L(0); PG8_BAR; PG8_MMA(1, 0, At, B0); PG8_MMA(1, 1, At, B1); PG8_BAR; PG8_SCHED;
;     ...
;         if constexpr (ALIGN_EPI) { if (wr == 0) PG8_BAR; }
	s_add_i32 s26, s33, s54
	v_lshl_add_u64 v[204:205], v[204:205], 0, s[10:11]
	s_mov_b32 m0, s26
	ds_read_b128 v[188:191], v152 offset:49152
	ds_read_b128 v[192:195], v152 offset:50176
	ds_read_b128 v[196:199], v152 offset:51200
	ds_read_b128 v[200:203], v152 offset:52224
	ds_read_b128 v[212:215], v152 offset:53248
	ds_read_b128 v[216:219], v152 offset:54272
	ds_read_b128 v[220:223], v152 offset:55296
	ds_read_b128 v[224:227], v152 offset:56320
	global_load_lds_dwordx4 v[204:205], off
	s_add_i32 m0, s26, 0x2000
	s_add_u32 s26, s50, 0x20080
	v_lshl_add_u64 v[204:205], v[206:207], 0, s[10:11]
	s_addc_u32 s27, s51, 0
	s_add_i32 s33, s77, s54
	global_load_lds_dwordx4 v[204:205], off
	v_lshl_add_u64 v[204:205], s[26:27], 0, v[132:133]
	s_mov_b32 m0, s33
	s_nop 0
	global_load_lds_dwordx4 v[204:205], off
	v_lshl_add_u64 v[204:205], s[26:27], 0, v[128:129]
	s_add_i32 m0, s33, 0x2000
	s_nop 0
	global_load_lds_dwordx4 v[204:205], off
	v_lshl_add_u64 v[204:205], v[208:209], 0, s[10:11]
	s_mov_b32 m0, s61
	s_nop 0
	global_load_lds_dwordx4 v[204:205], off
	v_lshl_add_u64 v[204:205], v[228:229], 0, s[10:11]
	s_mov_b32 m0, s62
	s_nop 0
	global_load_lds_dwordx4 v[204:205], off
	s_waitcnt vmcnt(8)
	s_waitcnt lgkmcnt(0)
	s_barrier
	s_setprio 1
	s_waitcnt lgkmcnt(0)
	v_mfma_f32_16x16x32_bf16 v[60:63], v[156:159], v[188:191], v[60:63]
	v_mfma_f32_16x16x32_bf16 v[56:59], v[164:167], v[188:191], v[56:59]
	v_mfma_f32_16x16x32_bf16 v[44:47], v[156:159], v[196:199], v[44:47]
	v_mfma_f32_16x16x32_bf16 v[40:43], v[164:167], v[196:199], v[40:43]
	v_mfma_f32_16x16x32_bf16 v[28:31], v[156:159], v[212:215], v[28:31]
	v_mfma_f32_16x16x32_bf16 v[24:27], v[164:167], v[212:215], v[24:27]
	v_mfma_f32_16x16x32_bf16 v[12:15], v[156:159], v[220:223], v[12:15]
	v_mfma_f32_16x16x32_bf16 v[8:11], v[164:167], v[220:223], v[8:11]
	v_mfma_f32_16x16x32_bf16 v[60:63], v[160:163], v[192:195], v[60:63]
	v_mfma_f32_16x16x32_bf16 v[56:59], v[168:171], v[192:195], v[56:59]
	v_mfma_f32_16x16x32_bf16 v[44:47], v[160:163], v[200:203], v[44:47]
	v_mfma_f32_16x16x32_bf16 v[40:43], v[168:171], v[200:203], v[40:43]
	v_mfma_f32_16x16x32_bf16 v[28:31], v[160:163], v[216:219], v[28:31]
	v_mfma_f32_16x16x32_bf16 v[24:27], v[168:171], v[216:219], v[24:27]
	v_mfma_f32_16x16x32_bf16 v[12:15], v[160:163], v[224:227], v[12:15]
	v_mfma_f32_16x16x32_bf16 v[8:11], v[168:171], v[224:227], v[8:11]
	s_setprio 0
	s_setprio 1
	v_mfma_f32_16x16x32_bf16 v[52:55], v[172:175], v[188:191], v[52:55]
	v_mfma_f32_16x16x32_bf16 v[48:51], v[180:183], v[188:191], v[48:51]
	v_mfma_f32_16x16x32_bf16 v[36:39], v[172:175], v[196:199], v[36:39]
	v_mfma_f32_16x16x32_bf16 v[32:35], v[180:183], v[196:199], v[32:35]
	v_mfma_f32_16x16x32_bf16 v[20:23], v[172:175], v[212:215], v[20:23]
	v_mfma_f32_16x16x32_bf16 v[16:19], v[180:183], v[212:215], v[16:19]
	v_mfma_f32_16x16x32_bf16 v[4:7], v[172:175], v[220:223], v[4:7]
	v_mfma_f32_16x16x32_bf16 v[0:3], v[180:183], v[220:223], v[0:3]
	v_mfma_f32_16x16x32_bf16 v[52:55], v[176:179], v[192:195], v[52:55]
	v_mfma_f32_16x16x32_bf16 v[48:51], v[184:187], v[192:195], v[48:51]
	v_mfma_f32_16x16x32_bf16 v[36:39], v[176:179], v[200:203], v[36:39]
	v_mfma_f32_16x16x32_bf16 v[32:35], v[184:187], v[200:203], v[32:35]
	v_mfma_f32_16x16x32_bf16 v[20:23], v[176:179], v[216:219], v[20:23]
	v_mfma_f32_16x16x32_bf16 v[16:19], v[184:187], v[216:219], v[16:19]
	v_mfma_f32_16x16x32_bf16 v[4:7], v[176:179], v[224:227], v[4:7]
	v_mfma_f32_16x16x32_bf16 v[0:3], v[184:187], v[224:227], v[0:3]
	s_setprio 0
	s_barrier
	s_add_i32 s76, s76, 2
	s_add_u32 s48, s48, 0x100
	s_addc_u32 s49, s49, 0
	s_add_u32 s74, s74, 0x100
	s_addc_u32 s75, s75, 0
	s_cmp_gt_u32 s76, 29
	s_cbranch_scc0 .LBB0_80
	s_add_i32 s99, s99, 1
	s_cmp_lt_u32 s99, 3
	s_cbranch_scc1 .Lapf_skip_0
	s_cmp_gt_u32 s99, 6
	s_cbranch_scc1 .Lapf_skip_0
	s_and_b32 s100, s2, 7
	s_lshl_b32 s100, s100, 24
	s_lshr_b32 s101, s2, 3
	s_lshl_b32 s101, s101, 18
	s_add_i32 s100, s100, s101
	s_lshl_b32 s101, s81, 9
	s_add_i32 s100, s100, s101
	s_sub_i32 s101, s99, 3
	s_lshl_b32 s101, s101, 13
	s_add_i32 s100, s100, s101
	s_add_i32 s100, s100, 0x9000000
	v_lshlrev_b32_e32 v247, 4, v252
	v_add_u32_e32 v247, s100, v247
	global_load_dwordx4 v[248:251], v247, s[18:19]
	global_load_dwordx4 v[248:251], v247, s[18:19] offset:1024
	global_load_dwordx4 v[248:251], v247, s[18:19] offset:2048
	global_load_dwordx4 v[248:251], v247, s[18:19] offset:3072
	v_add_u32_e32 v247, 0x1000, v247
	global_load_dwordx4 v[248:251], v247, s[18:19]
	global_load_dwordx4 v[248:251], v247, s[18:19] offset:1024
	global_load_dwordx4 v[248:251], v247, s[18:19] offset:2048
	global_load_dwordx4 v[248:251], v247, s[18:19] offset:3072
.Lapf_skip_0:
	s_and_b64 vcc, exec, s[14:15]
	s_cbranch_vccz .LBB0_83
	s_barrier

; #define PG8_LAS __attribute__((address_space(3)))
; #define PG8_STAGE(bufoff, gbase, voff) do { _Pragma("unroll") for (int _i = 0; _i < 2; ++_i) \
;         __builtin_amdgcn_global_load_lds((const unsigned*)((const char*)(gbase) + (voff)[_i]), (PG8_LAS unsigned*)(lds + (bufoff) + ldsw + _i * 8192), 16, 0, 0); } while (0)
; #define PG8_WAIT_V(n) asm volatile("s_waitcnt vmcnt(" #n ")" ::: "memory")
; #define PG8_BAR __builtin_amdgcn_s_barrier()
; template <class Epi, class Sched, bool ALIGN_EPI = false, bool SP2 = false>
; __device__ __forceinline__ void gemm_phase(PG8_LAS unsigned char* lds, const Gemm g, const Sched& S, const Epi& E, int tid_in) {
;     ...
;         PG8_WAIT_V(2); PG8_BAR;
;         PG8_STAGE(PG8_SB(1, 0), cB + kstep, voffB); PG8_STAGE(PG8_SA(1, 0), cA + kstep, voffA); PG8_STAGE(PG8_SB(1, 1), cB + hstepB + kstep, voffB);
;         PG8_WAIT_V(6); PG8_BAR;
;     __device__ __forceinline__ void operator()(const f32x4 (&acc)[2][2][4][2], const Unit& u, int wr, int wc, int fr, int fq) const {
;         const int lane = fr + 16 * fq; PG8_LAS unsigned char* stg = lds + STG_OFF + (wr * 4 + wc) * STG_WAVE;
;         const PG8_LAS float* rtab = (const PG8_LAS float*)(lds + RSTD_OFF) + ((u.pm >> 3) & 3) * 256;
.LBB0_384:
	s_mov_b64 s[12:13], 0x80
	s_and_b32 s9, s9, 3
	s_add_i32 m0, s51, 0x18000
	v_lshl_add_u64 v[6:7], v[6:7], 0, s[12:13]
	s_lshl_b32 s65, s33, 6
	s_lshl_b32 s15, s33, 13
	s_lshl_b32 s42, s9, 12
	s_waitcnt vmcnt(2)
	s_barrier
	global_load_lds_dwordx4 v[6:7], off
	v_lshl_add_u64 v[4:5], v[4:5], 0, s[12:13]
	s_add_i32 m0, s51, 0x1a000
	s_add_i32 s66, s51, 0x8000
	s_add_i32 s67, s51, 0xa000
	global_load_lds_dwordx4 v[4:5], off
	v_lshl_add_u64 v[0:1], v[0:1], 0, s[12:13]
	s_mov_b32 m0, s66
	s_add_u32 s26, s54, 0x20080
	global_load_lds_dwordx4 v[0:1], off
	v_lshl_add_u64 v[0:1], v[2:3], 0, s[12:13]
	s_mov_b32 m0, s67
	s_addc_u32 s27, s55, 0
	global_load_lds_dwordx4 v[0:1], off
	s_add_i32 m0, s51, 0x1c000
	v_lshl_add_u64 v[0:1], s[26:27], 0, v[130:131]
	global_load_lds_dwordx4 v[0:1], off
	v_lshl_add_u64 v[0:1], s[26:27], 0, v[134:135]
	s_add_i32 m0, s51, 0x1e000
	v_and_b32_e32 v2, 15, v8
	global_load_lds_dwordx4 v[0:1], off
	v_and_b32_e32 v3, 48, v8
	v_lshlrev_b32_e32 v1, 2, v2
	v_lshl_or_b32 v0, v2, 6, v3
	v_and_b32_e32 v4, 32, v1
	s_cmpk_lt_u32 s14, 0x100
	s_sext_i32_i16 s71, s8
	v_bitop3_b32 v5, v0, s15, v4 bitop3:0xde
	s_cselect_b64 s[14:15], -1, 0
	s_lshl_b32 s8, s33, 2
	s_or_b32 s8, s8, s9
	s_mul_i32 s26, s8, 0x900
	s_lshl_b32 s8, s33, 8
	s_add_i32 s8, s8, 0
	s_add_i32 s8, s8, 0x24800
	v_add_u32_e32 v149, s8, v1
	s_lshl_b32 s8, s9, 7
	s_add_u32 s8, s34, s8
	v_bitop3_b32 v146, v0, s42, v4 bitop3:0xde
	v_and_b32_e32 v0, 0x70, v12
	s_addc_u32 s9, s35, 0
	v_mov_b32_e32 v1, v131
	v_lshl_add_u64 v[136:137], s[8:9], 0, v[0:1]
	s_add_i32 s8, s26, 0
	s_add_i32 s8, s8, 0x20000
	s_movk_i32 s27, 0x90
	v_mov_b32_e32 v1, s8
	v_mad_u32_u24 v1, v2, s27, v1
	v_lshlrev_b32_e32 v2, 15, v9
	v_and_b32_e32 v2, 0xffff0000, v2
	v_lshl_add_u32 v2, v10, 12, v2
	v_and_b32_e32 v6, 1, v9
	v_lshl_or_b32 v2, v6, 6, v2
	v_lshl_add_u32 v138, v11, 1, v2
	v_lshlrev_b32_e32 v2, 15, v13
	v_and_b32_e32 v2, 0xffff0000, v2
	s_waitcnt vmcnt(6)
	v_bfe_u32 v147, v8, 3, 3
	v_lshl_add_u32 v2, v14, 12, v2
	v_and_b32_e32 v6, 1, v13
	v_mul_u32_u24_e32 v4, 0x90, v147
	v_add_u32_e32 v0, s8, v0
	v_lshl_or_b32 v2, v6, 6, v2
	s_add_i32 s68, 0, 0x10000
	s_add_i32 s69, 0, 0x14000
	v_or_b32_e32 v148, 8, v147
	v_mov_b32_e32 v139, v131
	v_lshl_add_u32 v140, v15, 1, v2
	v_mov_b32_e32 v141, v131
	v_mov_b64_e32 v[142:143], 0x1000
	v_mov_b64_e32 v[144:145], 0xfff
	v_add_u32_e32 v150, s68, v146
	v_add_u32_e32 v151, s69, v146
	v_add_u32_e32 v152, 0, v5
	v_add_u32_e32 v153, v1, v3
	v_add_u32_e32 v154, v0, v4
	s_movk_i32 s70, 0x4080
	s_barrier
	s_waitcnt vmcnt(0)
	s_mov_b32 s99, 0
	s_branch .LBB0_387

; #define PG8_STAGE(bufoff, gbase, voff) do { _Pragma("unroll") for (int _i = 0; _i < 2; ++_i) \
;         __builtin_amdgcn_global_load_lds((const unsigned*)((const char*)(gbase) + (voff)[_i]), (PG8_LAS unsigned*)(lds + (bufoff) + ldsw + _i * 8192), 16, 0, 0); } while (0)
; #define PG8_LDA(dst, b, h) do { _Pragma("unroll") for (int m = 0; m < 4; ++m) _Pragma("unroll") for (int k = 0; k < 2; ++k) dst[m][k] = *(const PG8_LAS bf16x8*)(lds + PG8_SA(b, h) + aoff + m * 2048 + k * 1024); } while (0)
; #define PG8_LDB(dst, b, h) do { _Pragma("unroll") for (int n = 0; n < 2; ++n) _Pragma("unroll") for (int k = 0; k < 2; ++k) dst[n][k] = *(const PG8_LAS bf16x8*)(lds + PG8_SB(b, h) + boff + n * 2048 + k * 1024); } while (0)
; #define PG8_MMA(ai, bj, At, Bt) do { __builtin_amdgcn_s_setprio(1); _Pragma("unroll") for (int m = 0; m < 4; ++m) _Pragma("unroll") for (int n = 0; n < 2; ++n) _Pragma("unroll") for (int k = 0; k < 2; ++k) \
;         acc[ai][bj][m][n] = __builtin_amdgcn_mfma_f32_16x16x32_bf16(Bt[n][k], At[m][k], acc[ai][bj][m][n], 0, 0, 0); __builtin_amdgcn_s_setprio(0); } while (0)
; #define PG8_WAIT_V(n) asm volatile("s_waitcnt vmcnt(" #n ")" ::: "memory")
; #define PG8_WAIT_L(n) asm volatile("s_waitcnt lgkmcnt(" #n ")" ::: "memory")
; #define PG8_BAR __builtin_amdgcn_s_barrier()
; #define PG8_SCHED __builtin_amdgcn_sched_barrier(0)
; template <class Epi, class Sched, bool ALIGN_EPI = false, bool SP2 = false>
; __device__ __forceinline__ void gemm_phase(PG8_LAS unsigned char* lds, const Gemm g, const Sched& S, const Epi& E, int tid_in) {
;     ...
;             PG8_LDB(B0, 0, 0); PG8_LDB(B1, 0, 1); PG8_SCHED; PG8_LDA(At, 0, 0); PG8_STAGE(PG8_SA(1, 1), a1 + hstep, voffA);
;             PG8_WAIT_V(8); PG8_WAIT_L(0); PG8_BAR; PG8_MMA(0, 0, At, B0); PG8_MMA(0, 1, At, B1); PG8_BAR; PG8_SCHED;
;             PG8_LDA(At, 0, 1); PG8_STAGE(PG8_SB(0, 0), b2, voffB); PG8_STAGE(PG8_SB(0, 1), b2 + hstepB, voffB); PG8_STAGE(PG8_SA(0, 0), a2, voffA);
;             PG8_WAIT_V(8); PG8_WAIT_L(0); PG8_BAR; PG8_MMA(1, 0, At, B0); PG8_MMA(1, 1, At, B1); PG8_BAR; PG8_SCHED;
.Lkb_skip_2:
.LBB0_394:
	ds_read_b128 v[156:159], v150
	ds_read_b128 v[160:163], v150 offset:1024
	ds_read_b128 v[164:167], v150 offset:2048
	ds_read_b128 v[168:171], v150 offset:3072
	ds_read_b128 v[172:175], v151
	ds_read_b128 v[176:179], v151 offset:1024
	ds_read_b128 v[180:183], v151 offset:2048
	ds_read_b128 v[184:187], v151 offset:3072
	s_add_u32 s26, s52, 0xfff80080
	s_addc_u32 s27, s53, -1
	s_cmp_eq_u32 s76, 28
	s_cselect_b32 s57, s45, s27
	s_cselect_b32 s56, s72, s26
	s_cselect_b32 s55, s43, s75
	s_cselect_b32 s54, s73, s74
	v_lshl_add_u64 v[208:209], s[52:53], 0, v[138:139]
	s_add_i32 m0, s51, 0xc000
	ds_read_b128 v[188:191], v152
	ds_read_b128 v[192:195], v152 offset:1024
	ds_read_b128 v[196:199], v152 offset:2048
	ds_read_b128 v[200:203], v152 offset:3072
	ds_read_b128 v[204:207], v152 offset:4096
	ds_read_b128 v[212:215], v152 offset:5120
	ds_read_b128 v[216:219], v152 offset:6144
	ds_read_b128 v[220:223], v152 offset:7168
	global_load_lds_dwordx4 v[208:209], off
	v_lshl_add_u64 v[208:209], s[52:53], 0, v[140:141]
	s_add_i32 m0, s51, 0xe000
	s_nop 0
	global_load_lds_dwordx4 v[208:209], off
	s_waitcnt vmcnt(8)
	s_waitcnt lgkmcnt(0)
	s_barrier
	s_setprio 1
	s_waitcnt lgkmcnt(0)
	v_mfma_f32_16x16x32_bf16 v[124:127], v[156:159], v[188:191], v[124:127]
	v_mfma_f32_16x16x32_bf16 v[120:123], v[164:167], v[188:191], v[120:123]
	v_mfma_f32_16x16x32_bf16 v[108:111], v[156:159], v[196:199], v[108:111]
	v_mfma_f32_16x16x32_bf16 v[104:107], v[164:167], v[196:199], v[104:107]
	v_mfma_f32_16x16x32_bf16 v[92:95], v[156:159], v[204:207], v[92:95]
	v_mfma_f32_16x16x32_bf16 v[88:91], v[164:167], v[204:207], v[88:91]
	v_mfma_f32_16x16x32_bf16 v[76:79], v[156:159], v[216:219], v[76:79]
	v_mfma_f32_16x16x32_bf16 v[72:75], v[164:167], v[216:219], v[72:75]
	v_mfma_f32_16x16x32_bf16 v[124:127], v[160:163], v[192:195], v[124:127]
	v_mfma_f32_16x16x32_bf16 v[120:123], v[168:171], v[192:195], v[120:123]
	v_mfma_f32_16x16x32_bf16 v[108:111], v[160:163], v[200:203], v[108:111]
	v_mfma_f32_16x16x32_bf16 v[104:107], v[168:171], v[200:203], v[104:107]
	v_mfma_f32_16x16x32_bf16 v[92:95], v[160:163], v[212:215], v[92:95]
	v_mfma_f32_16x16x32_bf16 v[88:91], v[168:171], v[212:215], v[88:91]
	v_mfma_f32_16x16x32_bf16 v[76:79], v[160:163], v[220:223], v[76:79]
	v_mfma_f32_16x16x32_bf16 v[72:75], v[168:171], v[220:223], v[72:75]
	s_setprio 0
	s_setprio 1
	v_mfma_f32_16x16x32_bf16 v[116:119], v[172:175], v[188:191], v[116:119]
	v_mfma_f32_16x16x32_bf16 v[112:115], v[180:183], v[188:191], v[112:115]
	v_mfma_f32_16x16x32_bf16 v[100:103], v[172:175], v[196:199], v[100:103]
	v_mfma_f32_16x16x32_bf16 v[96:99], v[180:183], v[196:199], v[96:99]
	v_mfma_f32_16x16x32_bf16 v[84:87], v[172:175], v[204:207], v[84:87]
	v_mfma_f32_16x16x32_bf16 v[80:83], v[180:183], v[204:207], v[80:83]
	v_mfma_f32_16x16x32_bf16 v[68:71], v[172:175], v[216:219], v[68:71]
	v_mfma_f32_16x16x32_bf16 v[64:67], v[180:183], v[216:219], v[64:67]
	v_mfma_f32_16x16x32_bf16 v[116:119], v[176:179], v[192:195], v[116:119]
	v_mfma_f32_16x16x32_bf16 v[112:115], v[184:187], v[192:195], v[112:115]
	v_mfma_f32_16x16x32_bf16 v[100:103], v[176:179], v[200:203], v[100:103]
	v_mfma_f32_16x16x32_bf16 v[96:99], v[184:187], v[200:203], v[96:99]
	v_mfma_f32_16x16x32_bf16 v[84:87], v[176:179], v[212:215], v[84:87]
	v_mfma_f32_16x16x32_bf16 v[80:83], v[184:187], v[212:215], v[80:83]
	v_mfma_f32_16x16x32_bf16 v[68:71], v[176:179], v[220:223], v[68:71]
	v_mfma_f32_16x16x32_bf16 v[64:67], v[184:187], v[220:223], v[64:67]
	s_setprio 0
	s_barrier
	s_add_i32 s26, s68, s60
	v_lshl_add_u64 v[208:209], s[54:55], 0, v[130:131]
	s_mov_b32 m0, s26
	ds_read_b128 v[188:191], v152 offset:16384
	ds_read_b128 v[192:195], v152 offset:17408
	ds_read_b128 v[196:199], v152 offset:18432
	ds_read_b128 v[200:203], v152 offset:19456
	ds_read_b128 v[204:207], v152 offset:20480
	ds_read_b128 v[212:215], v152 offset:21504
	ds_read_b128 v[216:219], v152 offset:22528
	ds_read_b128 v[220:223], v152 offset:23552
	global_load_lds_dwordx4 v[208:209], off
	s_add_i32 m0, s26, 0x2000
	s_add_u32 s26, s54, 0x20000
	v_lshl_add_u64 v[224:225], s[54:55], 0, v[134:135]
	s_addc_u32 s27, s55, 0
	s_add_i32 s33, s69, s60
	global_load_lds_dwordx4 v[224:225], off
	v_lshl_add_u64 v[226:227], s[26:27], 0, v[130:131]
	s_mov_b32 m0, s33
	v_lshl_add_u64 v[228:229], s[56:57], 0, v[132:133]
	global_load_lds_dwordx4 v[226:227], off
	v_lshl_add_u64 v[226:227], s[26:27], 0, v[134:135]
	s_add_i32 m0, s33, 0x2000
	s_nop 0
	global_load_lds_dwordx4 v[226:227], off
	v_lshl_add_u64 v[226:227], s[56:57], 0, v[128:129]
	s_mov_b32 m0, s51
	s_nop 0
	global_load_lds_dwordx4 v[226:227], off
	s_mov_b32 m0, s61
	s_nop 0
	global_load_lds_dwordx4 v[228:229], off
	s_waitcnt vmcnt(8)
	s_waitcnt lgkmcnt(0)
	s_barrier
; #define PG8_STAGE(bufoff, gbase, voff) do { _Pragma("unroll") for (int _i = 0; _i < 2; ++_i) \
;         __builtin_amdgcn_global_load_lds((const unsigned*)((const char*)(gbase) + (voff)[_i]), (PG8_LAS unsigned*)(lds + (bufoff) + ldsw + _i * 8192), 16, 0, 0); } while (0)
; #define PG8_LDA(dst, b, h) do { _Pragma("unroll") for (int m = 0; m < 4; ++m) _Pragma("unroll") for (int k = 0; k < 2; ++k) dst[m][k] = *(const PG8_LAS bf16x8*)(lds + PG8_SA(b, h) + aoff + m * 2048 + k * 1024); } while (0)
; #define PG8_LDB(dst, b, h) do { _Pragma("unroll") for (int n = 0; n < 2; ++n) _Pragma("unroll") for (int k = 0; k < 2; ++k) dst[n][k] = *(const PG8_LAS bf16x8*)(lds + PG8_SB(b, h) + boff + n * 2048 + k * 1024); } while (0)
; #define PG8_MMA(ai, bj, At, Bt) do { __builtin_amdgcn_s_setprio(1); _Pragma("unroll") for (int m = 0; m < 4; ++m) _Pragma("unroll") for (int n = 0; n < 2; ++n) _Pragma("unroll") for (int k = 0; k < 2; ++k) \
;         acc[ai][bj][m][n] = __builtin_amdgcn_mfma_f32_16x16x32_bf16(Bt[n][k], At[m][k], acc[ai][bj][m][n], 0, 0, 0); __builtin_amdgcn_s_setprio(0); } while (0)
; #define PG8_WAIT_V(n) asm volatile("s_waitcnt vmcnt(" #n ")" ::: "memory")
; #define PG8_WAIT_L(n) asm volatile("s_waitcnt lgkmcnt(" #n ")" ::: "memory")
; #define PG8_BAR __builtin_amdgcn_s_barrier()
; #define PG8_SCHED __builtin_amdgcn_sched_barrier(0)
; template <class Epi, class Sched, bool ALIGN_EPI = false, bool SP2 = false>
; __device__ __forceinline__ void gemm_phase(PG8_LAS unsigned char* lds, const Gemm g, const Sched& S, const Epi& E, int tid_in) {
;     ...
;             PG8_WAIT_V(8); PG8_WAIT_L(0); PG8_BAR; PG8_MMA(1, 0, At, B0); PG8_MMA(1, 1, At, B1); PG8_BAR; PG8_SCHED;
;             PG8_LDB(B0, 1, 0); PG8_LDB(B1, 1, 1); PG8_SCHED; PG8_LDA(At, 1, 0); PG8_STAGE(PG8_SA(0, 1), a2 + hstep, voffA);
;             PG8_WAIT_V(8); PG8_WAIT_L(0); PG8_BAR; PG8_MMA(0, 0, At, B0); PG8_MMA(0, 1, At, B1); PG8_BAR; PG8_SCHED;
	s_setprio 1
	s_waitcnt lgkmcnt(0)
	v_mfma_f32_16x16x32_bf16 v[60:63], v[156:159], v[188:191], v[60:63]
	v_mfma_f32_16x16x32_bf16 v[56:59], v[164:167], v[188:191], v[56:59]
	v_mfma_f32_16x16x32_bf16 v[44:47], v[156:159], v[196:199], v[44:47]
	v_mfma_f32_16x16x32_bf16 v[40:43], v[164:167], v[196:199], v[40:43]
	v_mfma_f32_16x16x32_bf16 v[28:31], v[156:159], v[204:207], v[28:31]
	v_mfma_f32_16x16x32_bf16 v[24:27], v[164:167], v[204:207], v[24:27]
	v_mfma_f32_16x16x32_bf16 v[12:15], v[156:159], v[216:219], v[12:15]
	v_mfma_f32_16x16x32_bf16 v[8:11], v[164:167], v[216:219], v[8:11]
	v_mfma_f32_16x16x32_bf16 v[60:63], v[160:163], v[192:195], v[60:63]
	v_mfma_f32_16x16x32_bf16 v[56:59], v[168:171], v[192:195], v[56:59]
	v_mfma_f32_16x16x32_bf16 v[44:47], v[160:163], v[200:203], v[44:47]
	v_mfma_f32_16x16x32_bf16 v[40:43], v[168:171], v[200:203], v[40:43]
	v_mfma_f32_16x16x32_bf16 v[28:31], v[160:163], v[212:215], v[28:31]
	v_mfma_f32_16x16x32_bf16 v[24:27], v[168:171], v[212:215], v[24:27]
	v_mfma_f32_16x16x32_bf16 v[12:15], v[160:163], v[220:223], v[12:15]
	v_mfma_f32_16x16x32_bf16 v[8:11], v[168:171], v[220:223], v[8:11]
	s_setprio 0
	s_setprio 1
	v_mfma_f32_16x16x32_bf16 v[52:55], v[172:175], v[188:191], v[52:55]
	v_mfma_f32_16x16x32_bf16 v[48:51], v[180:183], v[188:191], v[48:51]
	v_mfma_f32_16x16x32_bf16 v[36:39], v[172:175], v[196:199], v[36:39]
	v_mfma_f32_16x16x32_bf16 v[32:35], v[180:183], v[196:199], v[32:35]
	v_mfma_f32_16x16x32_bf16 v[20:23], v[172:175], v[204:207], v[20:23]
	v_mfma_f32_16x16x32_bf16 v[16:19], v[180:183], v[204:207], v[16:19]
	v_mfma_f32_16x16x32_bf16 v[4:7], v[172:175], v[216:219], v[4:7]
	v_mfma_f32_16x16x32_bf16 v[0:3], v[180:183], v[216:219], v[0:3]
	v_mfma_f32_16x16x32_bf16 v[52:55], v[176:179], v[192:195], v[52:55]
	v_mfma_f32_16x16x32_bf16 v[48:51], v[184:187], v[192:195], v[48:51]
	v_mfma_f32_16x16x32_bf16 v[36:39], v[176:179], v[200:203], v[36:39]
	v_mfma_f32_16x16x32_bf16 v[32:35], v[184:187], v[200:203], v[32:35]
	v_mfma_f32_16x16x32_bf16 v[20:23], v[176:179], v[212:215], v[20:23]
	v_mfma_f32_16x16x32_bf16 v[16:19], v[184:187], v[212:215], v[16:19]
	v_mfma_f32_16x16x32_bf16 v[4:7], v[176:179], v[220:223], v[4:7]
	v_mfma_f32_16x16x32_bf16 v[0:3], v[184:187], v[220:223], v[0:3]
	s_setprio 0
	s_barrier
	s_add_i32 s33, 0, 0x18000
	v_add_u32_e32 v155, s33, v146
	s_add_i32 s77, 0, 0x1c000
	ds_read_b128 v[156:159], v155
	ds_read_b128 v[160:163], v155 offset:1024
	ds_read_b128 v[164:167], v155 offset:2048
	ds_read_b128 v[168:171], v155 offset:3072
	v_add_u32_e32 v155, s77, v146
	ds_read_b128 v[172:175], v155
	ds_read_b128 v[176:179], v155 offset:1024
	ds_read_b128 v[180:183], v155 offset:2048
	ds_read_b128 v[184:187], v155 offset:3072
	s_add_u32 s26, s56, 0x80000
	s_addc_u32 s27, s57, 0
	s_mov_b32 m0, s62
	v_lshl_add_u64 v[230:231], s[26:27], 0, v[128:129]
	ds_read_b128 v[188:191], v152 offset:32768
	ds_read_b128 v[192:195], v152 offset:33792
	ds_read_b128 v[196:199], v152 offset:34816
	ds_read_b128 v[200:203], v152 offset:35840
	ds_read_b128 v[204:207], v152 offset:36864
	ds_read_b128 v[212:215], v152 offset:37888
	ds_read_b128 v[216:219], v152 offset:38912
	ds_read_b128 v[220:223], v152 offset:39936
	global_load_lds_dwordx4 v[230:231], off
	v_lshl_add_u64 v[230:231], s[26:27], 0, v[132:133]
	s_mov_b32 m0, s63
	s_nop 0
	global_load_lds_dwordx4 v[230:231], off
	s_waitcnt vmcnt(8)
	s_waitcnt lgkmcnt(0)
	s_barrier
	s_setprio 1
	s_waitcnt lgkmcnt(0)
	v_mfma_f32_16x16x32_bf16 v[124:127], v[156:159], v[188:191], v[124:127]
	v_mfma_f32_16x16x32_bf16 v[120:123], v[164:167], v[188:191], v[120:123]
	v_mfma_f32_16x16x32_bf16 v[108:111], v[156:159], v[196:199], v[108:111]
	v_mfma_f32_16x16x32_bf16 v[104:107], v[164:167], v[196:199], v[104:107]
	v_mfma_f32_16x16x32_bf16 v[92:95], v[156:159], v[204:207], v[92:95]
	v_mfma_f32_16x16x32_bf16 v[88:91], v[164:167], v[204:207], v[88:91]
	v_mfma_f32_16x16x32_bf16 v[76:79], v[156:159], v[216:219], v[76:79]
	v_mfma_f32_16x16x32_bf16 v[72:75], v[164:167], v[216:219], v[72:75]
	v_mfma_f32_16x16x32_bf16 v[124:127], v[160:163], v[192:195], v[124:127]
	v_mfma_f32_16x16x32_bf16 v[120:123], v[168:171], v[192:195], v[120:123]
	v_mfma_f32_16x16x32_bf16 v[108:111], v[160:163], v[200:203], v[108:111]
	v_mfma_f32_16x16x32_bf16 v[104:107], v[168:171], v[200:203], v[104:107]
	v_mfma_f32_16x16x32_bf16 v[92:95], v[160:163], v[212:215], v[92:95]
	v_mfma_f32_16x16x32_bf16 v[88:91], v[168:171], v[212:215], v[88:91]
	v_mfma_f32_16x16x32_bf16 v[76:79], v[160:163], v[220:223], v[76:79]
	v_mfma_f32_16x16x32_bf16 v[72:75], v[168:171], v[220:223], v[72:75]
	s_setprio 0
	s_setprio 1
	v_mfma_f32_16x16x32_bf16 v[116:119], v[172:175], v[188:191], v[116:119]
	v_mfma_f32_16x16x32_bf16 v[112:115], v[180:183], v[188:191], v[112:115]
	v_mfma_f32_16x16x32_bf16 v[100:103], v[172:175], v[196:199], v[100:103]
	v_mfma_f32_16x16x32_bf16 v[96:99], v[180:183], v[196:199], v[96:99]
	v_mfma_f32_16x16x32_bf16 v[84:87], v[172:175], v[204:207], v[84:87]
	v_mfma_f32_16x16x32_bf16 v[80:83], v[180:183], v[204:207], v[80:83]
	v_mfma_f32_16x16x32_bf16 v[68:71], v[172:175], v[216:219], v[68:71]
	v_mfma_f32_16x16x32_bf16 v[64:67], v[180:183], v[216:219], v[64:67]
	v_mfma_f32_16x16x32_bf16 v[116:119], v[176:179], v[192:195], v[116:119]
	v_mfma_f32_16x16x32_bf16 v[112:115], v[184:187], v[192:195], v[112:115]
	v_mfma_f32_16x16x32_bf16 v[100:103], v[176:179], v[200:203], v[100:103]
	v_mfma_f32_16x16x32_bf16 v[96:99], v[184:187], v[200:203], v[96:99]
	v_mfma_f32_16x16x32_bf16 v[84:87], v[176:179], v[212:215], v[84:87]
	v_mfma_f32_16x16x32_bf16 v[80:83], v[184:187], v[212:215], v[80:83]
	v_mfma_f32_16x16x32_bf16 v[68:71], v[176:179], v[220:223], v[68:71]
	v_mfma_f32_16x16x32_bf16 v[64:67], v[184:187], v[220:223], v[64:67]
	s_setprio 0
	s_barrier
; #define PG8_STAGE(bufoff, gbase, voff) do { _Pragma("unroll") for (int _i = 0; _i < 2; ++_i) \
;         __builtin_amdgcn_global_load_lds((const unsigned*)((const char*)(gbase) + (voff)[_i]), (PG8_LAS unsigned*)(lds + (bufoff) + ldsw + _i * 8192), 16, 0, 0); } while (0)
; #define PG8_LDA(dst, b, h) do { _Pragma("unroll") for (int m = 0; m < 4; ++m) _Pragma("unroll") for (int k = 0; k < 2; ++k) dst[m][k] = *(const PG8_LAS bf16x8*)(lds + PG8_SA(b, h) + aoff + m * 2048 + k * 1024); } while (0)
; #define PG8_MMA(ai, bj, At, Bt) do { __builtin_amdgcn_s_setprio(1); _Pragma("unroll") for (int m = 0; m < 4; ++m) _Pragma("unroll") for (int n = 0; n < 2; ++n) _Pragma("unroll") for (int k = 0; k < 2; ++k) \
;         acc[ai][bj][m][n] = __builtin_amdgcn_mfma_f32_16x16x32_bf16(Bt[n][k], At[m][k], acc[ai][bj][m][n], 0, 0, 0); __builtin_amdgcn_s_setprio(0); } while (0)
; #define PG8_WAIT_V(n) asm volatile("s_waitcnt vmcnt(" #n ")" ::: "memory")
; #define PG8_WAIT_L(n) asm volatile("s_waitcnt lgkmcnt(" #n ")" ::: "memory")
; #define PG8_BAR __builtin_amdgcn_s_barrier()
; #define PG8_SCHED __builtin_amdgcn_sched_barrier(0)
; template <class Epi, class Sched, bool ALIGN_EPI = false, bool SP2 = false>
; __device__ __forceinline__ void gemm_phase(PG8_LAS unsigned char* lds, const Gemm g, const Sched& S, const Epi& E, int tid_in) {
;     ...
;             PG8_WAIT_V(8); PG8_WAIT_L(0); PG8_BAR; PG8_MMA(0, 0, At, B0); PG8_MMA(0, 1, At, B1); PG8_BAR; PG8_SCHED;
;             PG8_LDA(At, 1, 1); PG8_STAGE(PG8_SB(1, 0), b3, voffB); PG8_STAGE(PG8_SB(1, 1), b3 + hstepB, voffB); PG8_STAGE(PG8_SA(1, 0), a3, voffA);
;             PG8_WAIT_V(8); PG8_WAIT_L(0); PG8_BAR; PG8_MMA(1, 0, At, B0); PG8_MMA(1, 1, At, B1); PG8_BAR; PG8_SCHED;
;     ...
;         if constexpr (ALIGN_EPI) { if (wr == 0) PG8_BAR; }
	s_add_i32 s26, s33, s60
	v_lshl_add_u64 v[208:209], v[208:209], 0, s[12:13]
	s_mov_b32 m0, s26
	ds_read_b128 v[188:191], v152 offset:49152
	ds_read_b128 v[192:195], v152 offset:50176
	ds_read_b128 v[196:199], v152 offset:51200
	ds_read_b128 v[200:203], v152 offset:52224
	ds_read_b128 v[204:207], v152 offset:53248
	ds_read_b128 v[212:215], v152 offset:54272
	ds_read_b128 v[216:219], v152 offset:55296
	ds_read_b128 v[220:223], v152 offset:56320
	global_load_lds_dwordx4 v[208:209], off
	s_add_i32 m0, s26, 0x2000
	s_add_u32 s26, s54, 0x20080
	v_lshl_add_u64 v[208:209], v[224:225], 0, s[12:13]
	s_addc_u32 s27, s55, 0
	s_add_i32 s33, s77, s60
	global_load_lds_dwordx4 v[208:209], off
	v_lshl_add_u64 v[208:209], s[26:27], 0, v[130:131]
	s_mov_b32 m0, s33
	s_nop 0
	global_load_lds_dwordx4 v[208:209], off
	v_lshl_add_u64 v[208:209], s[26:27], 0, v[134:135]
	s_add_i32 m0, s33, 0x2000
	s_nop 0
	global_load_lds_dwordx4 v[208:209], off
	v_lshl_add_u64 v[208:209], v[226:227], 0, s[12:13]
	s_mov_b32 m0, s66
	s_nop 0
	global_load_lds_dwordx4 v[208:209], off
	v_lshl_add_u64 v[208:209], v[228:229], 0, s[12:13]
	s_mov_b32 m0, s67
	s_nop 0
	global_load_lds_dwordx4 v[208:209], off
	s_waitcnt vmcnt(8)
	s_waitcnt lgkmcnt(0)
	s_barrier
	s_setprio 1
	s_waitcnt lgkmcnt(0)
	v_mfma_f32_16x16x32_bf16 v[60:63], v[156:159], v[188:191], v[60:63]
	v_mfma_f32_16x16x32_bf16 v[56:59], v[164:167], v[188:191], v[56:59]
	v_mfma_f32_16x16x32_bf16 v[44:47], v[156:159], v[196:199], v[44:47]
	v_mfma_f32_16x16x32_bf16 v[40:43], v[164:167], v[196:199], v[40:43]
	v_mfma_f32_16x16x32_bf16 v[28:31], v[156:159], v[204:207], v[28:31]
	v_mfma_f32_16x16x32_bf16 v[24:27], v[164:167], v[204:207], v[24:27]
	v_mfma_f32_16x16x32_bf16 v[12:15], v[156:159], v[216:219], v[12:15]
	v_mfma_f32_16x16x32_bf16 v[8:11], v[164:167], v[216:219], v[8:11]
	v_mfma_f32_16x16x32_bf16 v[60:63], v[160:163], v[192:195], v[60:63]
	v_mfma_f32_16x16x32_bf16 v[56:59], v[168:171], v[192:195], v[56:59]
	v_mfma_f32_16x16x32_bf16 v[44:47], v[160:163], v[200:203], v[44:47]
	v_mfma_f32_16x16x32_bf16 v[40:43], v[168:171], v[200:203], v[40:43]
	v_mfma_f32_16x16x32_bf16 v[28:31], v[160:163], v[212:215], v[28:31]
	v_mfma_f32_16x16x32_bf16 v[24:27], v[168:171], v[212:215], v[24:27]
	v_mfma_f32_16x16x32_bf16 v[12:15], v[160:163], v[220:223], v[12:15]
	v_mfma_f32_16x16x32_bf16 v[8:11], v[168:171], v[220:223], v[8:11]
	s_setprio 0
	s_setprio 1
	v_mfma_f32_16x16x32_bf16 v[52:55], v[172:175], v[188:191], v[52:55]
	v_mfma_f32_16x16x32_bf16 v[48:51], v[180:183], v[188:191], v[48:51]
	v_mfma_f32_16x16x32_bf16 v[36:39], v[172:175], v[196:199], v[36:39]
	v_mfma_f32_16x16x32_bf16 v[32:35], v[180:183], v[196:199], v[32:35]
	v_mfma_f32_16x16x32_bf16 v[20:23], v[172:175], v[204:207], v[20:23]
	v_mfma_f32_16x16x32_bf16 v[16:19], v[180:183], v[204:207], v[16:19]
	v_mfma_f32_16x16x32_bf16 v[4:7], v[172:175], v[216:219], v[4:7]
	v_mfma_f32_16x16x32_bf16 v[0:3], v[180:183], v[216:219], v[0:3]
	v_mfma_f32_16x16x32_bf16 v[52:55], v[176:179], v[192:195], v[52:55]
	v_mfma_f32_16x16x32_bf16 v[48:51], v[184:187], v[192:195], v[48:51]
	v_mfma_f32_16x16x32_bf16 v[36:39], v[176:179], v[200:203], v[36:39]
	v_mfma_f32_16x16x32_bf16 v[32:35], v[184:187], v[200:203], v[32:35]
	v_mfma_f32_16x16x32_bf16 v[20:23], v[176:179], v[212:215], v[20:23]
	v_mfma_f32_16x16x32_bf16 v[16:19], v[184:187], v[212:215], v[16:19]
	v_mfma_f32_16x16x32_bf16 v[4:7], v[176:179], v[220:223], v[4:7]
	v_mfma_f32_16x16x32_bf16 v[0:3], v[184:187], v[220:223], v[0:3]
	s_setprio 0
	s_barrier
	s_add_i32 s76, s76, 2
	s_add_u32 s52, s52, 0x100
	s_addc_u32 s53, s53, 0
	s_add_u32 s74, s74, 0x100
	s_addc_u32 s75, s75, 0
	s_cmp_gt_u32 s76, 29
	s_cbranch_scc0 .LBB0_394
	s_add_i32 s99, s99, 1
	s_cmp_lt_u32 s99, 5
	s_cbranch_scc1 .Lapf_skip_2
	s_cmp_gt_u32 s99, 8
	s_cbranch_scc1 .Lapf_skip_2
	s_and_b32 s100, s2, 7
	s_lshl_b32 s100, s100, 24
	s_lshr_b32 s101, s2, 3
	s_lshl_b32 s101, s101, 18
	s_add_i32 s100, s100, s101
	s_lshl_b32 s101, s81, 9
	s_add_i32 s100, s100, s101
	s_sub_i32 s101, s99, 5
	s_lshl_b32 s101, s101, 13
	s_add_i32 s100, s100, s101
	s_add_i32 s100, s100, 0x11000000
	v_lshlrev_b32_e32 v247, 4, v252
	v_add_u32_e32 v247, s100, v247
	global_load_dwordx4 v[248:251], v247, s[18:19]
	global_load_dwordx4 v[248:251], v247, s[18:19] offset:1024
	global_load_dwordx4 v[248:251], v247, s[18:19] offset:2048
	global_load_dwordx4 v[248:251], v247, s[18:19] offset:3072
	v_add_u32_e32 v247, 0x1000, v247
	global_load_dwordx4 v[248:251], v247, s[18:19]
	global_load_dwordx4 v[248:251], v247, s[18:19] offset:1024
	global_load_dwordx4 v[248:251], v247, s[18:19] offset:2048
	global_load_dwordx4 v[248:251], v247, s[18:19] offset:3072

; #define PG8_LAS __attribute__((address_space(3)))
; #define PG8_STAGE(bufoff, gbase, voff) do { _Pragma("unroll") for (int _i = 0; _i < 2; ++_i) \
;         __builtin_amdgcn_global_load_lds((const unsigned*)((const char*)(gbase) + (voff)[_i]), (PG8_LAS unsigned*)(lds + (bufoff) + ldsw + _i * 8192), 16, 0, 0); } while (0)
; #define PG8_WAIT_V(n) asm volatile("s_waitcnt vmcnt(" #n ")" ::: "memory")
; #define PG8_BAR __builtin_amdgcn_s_barrier()
; template <class Epi, class Sched, bool ALIGN_EPI = false, bool SP2 = false>
; __device__ __forceinline__ void gemm_phase(PG8_LAS unsigned char* lds, const Gemm g, const Sched& S, const Epi& E, int tid_in) {
;     ...
;         PG8_WAIT_V(2); PG8_BAR;
;         PG8_STAGE(PG8_SB(1, 0), cB + kstep, voffB); PG8_STAGE(PG8_SA(1, 0), cA + kstep, voffA); PG8_STAGE(PG8_SB(1, 1), cB + hstepB + kstep, voffB);
;         PG8_WAIT_V(6); PG8_BAR;
;     __device__ __forceinline__ void operator()(const f32x4 (&acc)[2][2][4][2], const Unit& u, int wr, int wc, int fr, int fq) const {
;         const int lane = fr + 16 * fq; PG8_LAS unsigned char* stg = lds + STG_OFF + (wr * 4 + wc) * STG_WAVE;
;         const PG8_LAS float* rtab = (const PG8_LAS float*)(lds + RSTD_OFF) + ((u.pm >> 3) & 3) * 256;
.LBB0_859:
	s_mov_b64 s[12:13], 0x80
	s_and_b32 s9, s9, 3
	s_add_i32 m0, s49, 0x18000
	v_lshl_add_u64 v[6:7], v[6:7], 0, s[12:13]
	s_lshl_b32 s61, s33, 6
	s_lshl_b32 s37, s33, 13
	s_lshl_b32 s38, s9, 12
	s_waitcnt vmcnt(2)
	s_barrier
	global_load_lds_dwordx4 v[6:7], off
	v_lshl_add_u64 v[4:5], v[4:5], 0, s[12:13]
	s_add_i32 m0, s49, 0x1a000
	s_add_i32 s62, s49, 0x8000
	s_add_i32 s63, s49, 0xa000
	global_load_lds_dwordx4 v[4:5], off
	v_lshl_add_u64 v[0:1], v[0:1], 0, s[12:13]
	s_mov_b32 m0, s62
	s_add_u32 s26, s52, 0x20080
	global_load_lds_dwordx4 v[0:1], off
	v_lshl_add_u64 v[0:1], v[2:3], 0, s[12:13]
	s_mov_b32 m0, s63
	s_addc_u32 s27, s53, 0
	global_load_lds_dwordx4 v[0:1], off
	s_add_i32 m0, s49, 0x1c000
	v_lshl_add_u64 v[0:1], s[26:27], 0, v[130:131]
	global_load_lds_dwordx4 v[0:1], off
	v_lshl_add_u64 v[0:1], s[26:27], 0, v[134:135]
	s_add_i32 m0, s49, 0x1e000
	v_and_b32_e32 v2, 15, v8
	global_load_lds_dwordx4 v[0:1], off
	v_and_b32_e32 v3, 48, v8
	v_lshlrev_b32_e32 v1, 2, v2
	v_lshl_or_b32 v0, v2, 6, v3
	v_and_b32_e32 v4, 32, v1
	s_cmpk_lt_u32 s36, 0x100
	s_sext_i32_i16 s67, s8
	v_bitop3_b32 v5, v0, s37, v4 bitop3:0xde
	s_cselect_b64 s[36:37], -1, 0
	s_lshl_b32 s8, s33, 2
	s_or_b32 s8, s8, s9
	s_mul_i32 s26, s8, 0x900
	s_lshl_b32 s8, s33, 8
	s_add_i32 s8, s8, 0
	s_add_i32 s8, s8, 0x24800
	v_add_u32_e32 v149, s8, v1
	s_lshl_b32 s8, s9, 7
	s_add_u32 s8, s34, s8
	v_bitop3_b32 v146, v0, s38, v4 bitop3:0xde
	v_and_b32_e32 v0, 0x70, v12
	s_addc_u32 s9, s35, 0
	v_mov_b32_e32 v1, v131
	v_lshl_add_u64 v[136:137], s[8:9], 0, v[0:1]
	s_add_i32 s8, s26, 0
	s_add_i32 s8, s8, 0x20000
	s_movk_i32 s27, 0x90
	v_mov_b32_e32 v1, s8
	v_mad_u32_u24 v1, v2, s27, v1
	v_lshlrev_b32_e32 v2, 15, v9
	v_and_b32_e32 v2, 0xffff0000, v2
	v_lshl_add_u32 v2, v10, 12, v2
	v_and_b32_e32 v6, 1, v9
	v_lshl_or_b32 v2, v6, 6, v2
	v_lshl_add_u32 v138, v11, 1, v2
	v_lshlrev_b32_e32 v2, 15, v13
	v_and_b32_e32 v2, 0xffff0000, v2
	s_waitcnt vmcnt(6)
	v_bfe_u32 v147, v8, 3, 3
	v_lshl_add_u32 v2, v14, 12, v2
	v_and_b32_e32 v6, 1, v13
	v_mul_u32_u24_e32 v4, 0x90, v147
	v_add_u32_e32 v0, s8, v0
	v_lshl_or_b32 v2, v6, 6, v2
	s_add_i32 s64, 0, 0x10000
	s_add_i32 s65, 0, 0x14000
	v_or_b32_e32 v148, 8, v147
	v_mov_b32_e32 v139, v131
	v_lshl_add_u32 v140, v15, 1, v2
	v_mov_b32_e32 v141, v131
	v_mov_b64_e32 v[142:143], 0x1000
	v_mov_b64_e32 v[144:145], 0xfff
	v_add_u32_e32 v150, s64, v146
	v_add_u32_e32 v151, s65, v146
	v_add_u32_e32 v152, 0, v5
	v_add_u32_e32 v153, v1, v3
	v_add_u32_e32 v154, v0, v4
	s_movk_i32 s66, 0x4080
	s_barrier
	s_waitcnt vmcnt(0)
	s_mov_b32 s99, 0
	s_branch .LBB0_862

; #define PG8_STAGE(bufoff, gbase, voff) do { _Pragma("unroll") for (int _i = 0; _i < 2; ++_i) \
;         __builtin_amdgcn_global_load_lds((const unsigned*)((const char*)(gbase) + (voff)[_i]), (PG8_LAS unsigned*)(lds + (bufoff) + ldsw + _i * 8192), 16, 0, 0); } while (0)
; #define PG8_LDA(dst, b, h) do { _Pragma("unroll") for (int m = 0; m < 4; ++m) _Pragma("unroll") for (int k = 0; k < 2; ++k) dst[m][k] = *(const PG8_LAS bf16x8*)(lds + PG8_SA(b, h) + aoff + m * 2048 + k * 1024); } while (0)
; #define PG8_LDB(dst, b, h) do { _Pragma("unroll") for (int n = 0; n < 2; ++n) _Pragma("unroll") for (int k = 0; k < 2; ++k) dst[n][k] = *(const PG8_LAS bf16x8*)(lds + PG8_SB(b, h) + boff + n * 2048 + k * 1024); } while (0)
; #define PG8_MMA(ai, bj, At, Bt) do { __builtin_amdgcn_s_setprio(1); _Pragma("unroll") for (int m = 0; m < 4; ++m) _Pragma("unroll") for (int n = 0; n < 2; ++n) _Pragma("unroll") for (int k = 0; k < 2; ++k) \
;         acc[ai][bj][m][n] = __builtin_amdgcn_mfma_f32_16x16x32_bf16(Bt[n][k], At[m][k], acc[ai][bj][m][n], 0, 0, 0); __builtin_amdgcn_s_setprio(0); } while (0)
; #define PG8_WAIT_V(n) asm volatile("s_waitcnt vmcnt(" #n ")" ::: "memory")
; #define PG8_WAIT_L(n) asm volatile("s_waitcnt lgkmcnt(" #n ")" ::: "memory")
; #define PG8_BAR __builtin_amdgcn_s_barrier()
; #define PG8_SCHED __builtin_amdgcn_sched_barrier(0)
; template <class Epi, class Sched, bool ALIGN_EPI = false, bool SP2 = false>
; __device__ __forceinline__ void gemm_phase(PG8_LAS unsigned char* lds, const Gemm g, const Sched& S, const Epi& E, int tid_in) {
;     ...
;             PG8_LDB(B0, 0, 0); PG8_LDB(B1, 0, 1); PG8_SCHED; PG8_LDA(At, 0, 0); PG8_STAGE(PG8_SA(1, 1), a1 + hstep, voffA);
;             PG8_WAIT_V(8); PG8_WAIT_L(0); PG8_BAR; PG8_MMA(0, 0, At, B0); PG8_MMA(0, 1, At, B1); PG8_BAR; PG8_SCHED;
;             PG8_LDA(At, 0, 1); PG8_STAGE(PG8_SB(0, 0), b2, voffB); PG8_STAGE(PG8_SB(0, 1), b2 + hstepB, voffB); PG8_STAGE(PG8_SA(0, 0), a2, voffA);
;             PG8_WAIT_V(8); PG8_WAIT_L(0); PG8_BAR; PG8_MMA(1, 0, At, B0); PG8_MMA(1, 1, At, B1); PG8_BAR; PG8_SCHED;
.Lkb_skip_6:
.LBB0_869:
	ds_read_b128 v[156:159], v150
	ds_read_b128 v[160:163], v150 offset:1024
	ds_read_b128 v[164:167], v150 offset:2048
	ds_read_b128 v[168:171], v150 offset:3072
	ds_read_b128 v[172:175], v151
	ds_read_b128 v[176:179], v151 offset:1024
	ds_read_b128 v[180:183], v151 offset:2048
	ds_read_b128 v[184:187], v151 offset:3072
	s_add_u32 s26, s50, 0xfff80080
	s_addc_u32 s27, s51, -1
	s_cmp_eq_u32 s72, 28
	s_cselect_b32 s55, s41, s27
	s_cselect_b32 s54, s68, s26
	s_cselect_b32 s53, s39, s71
	s_cselect_b32 s52, s69, s70
	v_lshl_add_u64 v[220:221], s[50:51], 0, v[138:139]
	s_add_i32 m0, s49, 0xc000
	ds_read_b128 v[188:191], v152
	ds_read_b128 v[192:195], v152 offset:1024
	ds_read_b128 v[196:199], v152 offset:2048
	ds_read_b128 v[200:203], v152 offset:3072
	ds_read_b128 v[204:207], v152 offset:4096
	ds_read_b128 v[208:211], v152 offset:5120
	ds_read_b128 v[212:215], v152 offset:6144
	ds_read_b128 v[216:219], v152 offset:7168
	global_load_lds_dwordx4 v[220:221], off
	v_lshl_add_u64 v[220:221], s[50:51], 0, v[140:141]
	s_add_i32 m0, s49, 0xe000
	s_nop 0
	global_load_lds_dwordx4 v[220:221], off
	s_waitcnt vmcnt(8)
	s_waitcnt lgkmcnt(0)
	s_barrier
	s_setprio 1
	s_waitcnt lgkmcnt(0)
	v_mfma_f32_16x16x32_bf16 v[124:127], v[156:159], v[188:191], v[124:127]
	v_mfma_f32_16x16x32_bf16 v[120:123], v[164:167], v[188:191], v[120:123]
	v_mfma_f32_16x16x32_bf16 v[108:111], v[156:159], v[196:199], v[108:111]
	v_mfma_f32_16x16x32_bf16 v[104:107], v[164:167], v[196:199], v[104:107]
	v_mfma_f32_16x16x32_bf16 v[92:95], v[156:159], v[204:207], v[92:95]
	v_mfma_f32_16x16x32_bf16 v[88:91], v[164:167], v[204:207], v[88:91]
	v_mfma_f32_16x16x32_bf16 v[76:79], v[156:159], v[212:215], v[76:79]
	v_mfma_f32_16x16x32_bf16 v[72:75], v[164:167], v[212:215], v[72:75]
	v_mfma_f32_16x16x32_bf16 v[124:127], v[160:163], v[192:195], v[124:127]
	v_mfma_f32_16x16x32_bf16 v[120:123], v[168:171], v[192:195], v[120:123]
	v_mfma_f32_16x16x32_bf16 v[108:111], v[160:163], v[200:203], v[108:111]
	v_mfma_f32_16x16x32_bf16 v[104:107], v[168:171], v[200:203], v[104:107]
	v_mfma_f32_16x16x32_bf16 v[92:95], v[160:163], v[208:211], v[92:95]
	v_mfma_f32_16x16x32_bf16 v[88:91], v[168:171], v[208:211], v[88:91]
	v_mfma_f32_16x16x32_bf16 v[76:79], v[160:163], v[216:219], v[76:79]
	v_mfma_f32_16x16x32_bf16 v[72:75], v[168:171], v[216:219], v[72:75]
	s_setprio 0
	s_setprio 1
	v_mfma_f32_16x16x32_bf16 v[116:119], v[172:175], v[188:191], v[116:119]
	v_mfma_f32_16x16x32_bf16 v[112:115], v[180:183], v[188:191], v[112:115]
	v_mfma_f32_16x16x32_bf16 v[100:103], v[172:175], v[196:199], v[100:103]
	v_mfma_f32_16x16x32_bf16 v[96:99], v[180:183], v[196:199], v[96:99]
	v_mfma_f32_16x16x32_bf16 v[84:87], v[172:175], v[204:207], v[84:87]
	v_mfma_f32_16x16x32_bf16 v[80:83], v[180:183], v[204:207], v[80:83]
	v_mfma_f32_16x16x32_bf16 v[68:71], v[172:175], v[212:215], v[68:71]
	v_mfma_f32_16x16x32_bf16 v[64:67], v[180:183], v[212:215], v[64:67]
	v_mfma_f32_16x16x32_bf16 v[116:119], v[176:179], v[192:195], v[116:119]
	v_mfma_f32_16x16x32_bf16 v[112:115], v[184:187], v[192:195], v[112:115]
	v_mfma_f32_16x16x32_bf16 v[100:103], v[176:179], v[200:203], v[100:103]
	v_mfma_f32_16x16x32_bf16 v[96:99], v[184:187], v[200:203], v[96:99]
	v_mfma_f32_16x16x32_bf16 v[84:87], v[176:179], v[208:211], v[84:87]
	v_mfma_f32_16x16x32_bf16 v[80:83], v[184:187], v[208:211], v[80:83]
	v_mfma_f32_16x16x32_bf16 v[68:71], v[176:179], v[216:219], v[68:71]
	v_mfma_f32_16x16x32_bf16 v[64:67], v[184:187], v[216:219], v[64:67]
	s_setprio 0
	s_barrier
	s_add_i32 s26, s64, s56
	v_lshl_add_u64 v[220:221], s[52:53], 0, v[130:131]
	s_mov_b32 m0, s26
	ds_read_b128 v[188:191], v152 offset:16384
	ds_read_b128 v[192:195], v152 offset:17408
	ds_read_b128 v[196:199], v152 offset:18432
	ds_read_b128 v[200:203], v152 offset:19456
	ds_read_b128 v[204:207], v152 offset:20480
	ds_read_b128 v[208:211], v152 offset:21504
	ds_read_b128 v[212:215], v152 offset:22528
	ds_read_b128 v[216:219], v152 offset:23552
	global_load_lds_dwordx4 v[220:221], off
	s_add_i32 m0, s26, 0x2000
	s_add_u32 s26, s52, 0x20000
	v_lshl_add_u64 v[222:223], s[52:53], 0, v[134:135]
	s_addc_u32 s27, s53, 0
	s_add_i32 s33, s65, s56
	global_load_lds_dwordx4 v[222:223], off
	v_lshl_add_u64 v[224:225], s[26:27], 0, v[130:131]
	s_mov_b32 m0, s33
	v_lshl_add_u64 v[226:227], s[54:55], 0, v[132:133]
	global_load_lds_dwordx4 v[224:225], off
	v_lshl_add_u64 v[224:225], s[26:27], 0, v[134:135]
	s_add_i32 m0, s33, 0x2000
	s_nop 0
	global_load_lds_dwordx4 v[224:225], off
	v_lshl_add_u64 v[224:225], s[54:55], 0, v[128:129]
	s_mov_b32 m0, s49
	s_nop 0
	global_load_lds_dwordx4 v[224:225], off
	s_mov_b32 m0, s57
	s_nop 0
	global_load_lds_dwordx4 v[226:227], off
	s_waitcnt vmcnt(8)
	s_waitcnt lgkmcnt(0)
	s_barrier
; #define PG8_STAGE(bufoff, gbase, voff) do { _Pragma("unroll") for (int _i = 0; _i < 2; ++_i) \
;         __builtin_amdgcn_global_load_lds((const unsigned*)((const char*)(gbase) + (voff)[_i]), (PG8_LAS unsigned*)(lds + (bufoff) + ldsw + _i * 8192), 16, 0, 0); } while (0)
; #define PG8_LDA(dst, b, h) do { _Pragma("unroll") for (int m = 0; m < 4; ++m) _Pragma("unroll") for (int k = 0; k < 2; ++k) dst[m][k] = *(const PG8_LAS bf16x8*)(lds + PG8_SA(b, h) + aoff + m * 2048 + k * 1024); } while (0)
; #define PG8_LDB(dst, b, h) do { _Pragma("unroll") for (int n = 0; n < 2; ++n) _Pragma("unroll") for (int k = 0; k < 2; ++k) dst[n][k] = *(const PG8_LAS bf16x8*)(lds + PG8_SB(b, h) + boff + n * 2048 + k * 1024); } while (0)
; #define PG8_MMA(ai, bj, At, Bt) do { __builtin_amdgcn_s_setprio(1); _Pragma("unroll") for (int m = 0; m < 4; ++m) _Pragma("unroll") for (int n = 0; n < 2; ++n) _Pragma("unroll") for (int k = 0; k < 2; ++k) \
;         acc[ai][bj][m][n] = __builtin_amdgcn_mfma_f32_16x16x32_bf16(Bt[n][k], At[m][k], acc[ai][bj][m][n], 0, 0, 0); __builtin_amdgcn_s_setprio(0); } while (0)
; #define PG8_WAIT_V(n) asm volatile("s_waitcnt vmcnt(" #n ")" ::: "memory")
; #define PG8_WAIT_L(n) asm volatile("s_waitcnt lgkmcnt(" #n ")" ::: "memory")
; #define PG8_BAR __builtin_amdgcn_s_barrier()
; #define PG8_SCHED __builtin_amdgcn_sched_barrier(0)
; template <class Epi, class Sched, bool ALIGN_EPI = false, bool SP2 = false>
; __device__ __forceinline__ void gemm_phase(PG8_LAS unsigned char* lds, const Gemm g, const Sched& S, const Epi& E, int tid_in) {
;     ...
;             PG8_WAIT_V(8); PG8_WAIT_L(0); PG8_BAR; PG8_MMA(1, 0, At, B0); PG8_MMA(1, 1, At, B1); PG8_BAR; PG8_SCHED;
;             PG8_LDB(B0, 1, 0); PG8_LDB(B1, 1, 1); PG8_SCHED; PG8_LDA(At, 1, 0); PG8_STAGE(PG8_SA(0, 1), a2 + hstep, voffA);
;             PG8_WAIT_V(8); PG8_WAIT_L(0); PG8_BAR; PG8_MMA(0, 0, At, B0); PG8_MMA(0, 1, At, B1); PG8_BAR; PG8_SCHED;
	s_setprio 1
	s_waitcnt lgkmcnt(0)
	v_mfma_f32_16x16x32_bf16 v[60:63], v[156:159], v[188:191], v[60:63]
	v_mfma_f32_16x16x32_bf16 v[56:59], v[164:167], v[188:191], v[56:59]
	v_mfma_f32_16x16x32_bf16 v[44:47], v[156:159], v[196:199], v[44:47]
	v_mfma_f32_16x16x32_bf16 v[40:43], v[164:167], v[196:199], v[40:43]
	v_mfma_f32_16x16x32_bf16 v[28:31], v[156:159], v[204:207], v[28:31]
	v_mfma_f32_16x16x32_bf16 v[24:27], v[164:167], v[204:207], v[24:27]
	v_mfma_f32_16x16x32_bf16 v[12:15], v[156:159], v[212:215], v[12:15]
	v_mfma_f32_16x16x32_bf16 v[8:11], v[164:167], v[212:215], v[8:11]
	v_mfma_f32_16x16x32_bf16 v[60:63], v[160:163], v[192:195], v[60:63]
	v_mfma_f32_16x16x32_bf16 v[56:59], v[168:171], v[192:195], v[56:59]
	v_mfma_f32_16x16x32_bf16 v[44:47], v[160:163], v[200:203], v[44:47]
	v_mfma_f32_16x16x32_bf16 v[40:43], v[168:171], v[200:203], v[40:43]
	v_mfma_f32_16x16x32_bf16 v[28:31], v[160:163], v[208:211], v[28:31]
	v_mfma_f32_16x16x32_bf16 v[24:27], v[168:171], v[208:211], v[24:27]
	v_mfma_f32_16x16x32_bf16 v[12:15], v[160:163], v[216:219], v[12:15]
	v_mfma_f32_16x16x32_bf16 v[8:11], v[168:171], v[216:219], v[8:11]
	s_setprio 0
	s_setprio 1
	v_mfma_f32_16x16x32_bf16 v[52:55], v[172:175], v[188:191], v[52:55]
	v_mfma_f32_16x16x32_bf16 v[48:51], v[180:183], v[188:191], v[48:51]
	v_mfma_f32_16x16x32_bf16 v[36:39], v[172:175], v[196:199], v[36:39]
	v_mfma_f32_16x16x32_bf16 v[32:35], v[180:183], v[196:199], v[32:35]
	v_mfma_f32_16x16x32_bf16 v[20:23], v[172:175], v[204:207], v[20:23]
	v_mfma_f32_16x16x32_bf16 v[16:19], v[180:183], v[204:207], v[16:19]
	v_mfma_f32_16x16x32_bf16 v[4:7], v[172:175], v[212:215], v[4:7]
	v_mfma_f32_16x16x32_bf16 v[0:3], v[180:183], v[212:215], v[0:3]
	v_mfma_f32_16x16x32_bf16 v[52:55], v[176:179], v[192:195], v[52:55]
	v_mfma_f32_16x16x32_bf16 v[48:51], v[184:187], v[192:195], v[48:51]
	v_mfma_f32_16x16x32_bf16 v[36:39], v[176:179], v[200:203], v[36:39]
	v_mfma_f32_16x16x32_bf16 v[32:35], v[184:187], v[200:203], v[32:35]
	v_mfma_f32_16x16x32_bf16 v[20:23], v[176:179], v[208:211], v[20:23]
	v_mfma_f32_16x16x32_bf16 v[16:19], v[184:187], v[208:211], v[16:19]
	v_mfma_f32_16x16x32_bf16 v[4:7], v[176:179], v[216:219], v[4:7]
	v_mfma_f32_16x16x32_bf16 v[0:3], v[184:187], v[216:219], v[0:3]
	s_setprio 0
	s_barrier
	s_add_i32 s33, 0, 0x18000
	v_add_u32_e32 v155, s33, v146
	s_add_i32 s73, 0, 0x1c000
	ds_read_b128 v[156:159], v155
	ds_read_b128 v[160:163], v155 offset:1024
	ds_read_b128 v[164:167], v155 offset:2048
	ds_read_b128 v[168:171], v155 offset:3072
	v_add_u32_e32 v155, s73, v146
	ds_read_b128 v[172:175], v155
	ds_read_b128 v[176:179], v155 offset:1024
	ds_read_b128 v[180:183], v155 offset:2048
	ds_read_b128 v[184:187], v155 offset:3072
	s_add_u32 s26, s54, 0x80000
	s_addc_u32 s27, s55, 0
	s_mov_b32 m0, s58
	v_lshl_add_u64 v[228:229], s[26:27], 0, v[128:129]
	ds_read_b128 v[188:191], v152 offset:32768
	ds_read_b128 v[192:195], v152 offset:33792
	ds_read_b128 v[196:199], v152 offset:34816
	ds_read_b128 v[200:203], v152 offset:35840
	ds_read_b128 v[204:207], v152 offset:36864
	ds_read_b128 v[208:211], v152 offset:37888
	ds_read_b128 v[212:215], v152 offset:38912
	ds_read_b128 v[216:219], v152 offset:39936
	global_load_lds_dwordx4 v[228:229], off
	v_lshl_add_u64 v[228:229], s[26:27], 0, v[132:133]
	s_mov_b32 m0, s59
	s_nop 0
	global_load_lds_dwordx4 v[228:229], off
	s_waitcnt vmcnt(8)
	s_waitcnt lgkmcnt(0)
	s_barrier
	s_setprio 1
	s_waitcnt lgkmcnt(0)
	v_mfma_f32_16x16x32_bf16 v[124:127], v[156:159], v[188:191], v[124:127]
	v_mfma_f32_16x16x32_bf16 v[120:123], v[164:167], v[188:191], v[120:123]
	v_mfma_f32_16x16x32_bf16 v[108:111], v[156:159], v[196:199], v[108:111]
	v_mfma_f32_16x16x32_bf16 v[104:107], v[164:167], v[196:199], v[104:107]
	v_mfma_f32_16x16x32_bf16 v[92:95], v[156:159], v[204:207], v[92:95]
	v_mfma_f32_16x16x32_bf16 v[88:91], v[164:167], v[204:207], v[88:91]
	v_mfma_f32_16x16x32_bf16 v[76:79], v[156:159], v[212:215], v[76:79]
	v_mfma_f32_16x16x32_bf16 v[72:75], v[164:167], v[212:215], v[72:75]
	v_mfma_f32_16x16x32_bf16 v[124:127], v[160:163], v[192:195], v[124:127]
	v_mfma_f32_16x16x32_bf16 v[120:123], v[168:171], v[192:195], v[120:123]
	v_mfma_f32_16x16x32_bf16 v[108:111], v[160:163], v[200:203], v[108:111]
	v_mfma_f32_16x16x32_bf16 v[104:107], v[168:171], v[200:203], v[104:107]
	v_mfma_f32_16x16x32_bf16 v[92:95], v[160:163], v[208:211], v[92:95]
	v_mfma_f32_16x16x32_bf16 v[88:91], v[168:171], v[208:211], v[88:91]
	v_mfma_f32_16x16x32_bf16 v[76:79], v[160:163], v[216:219], v[76:79]
	v_mfma_f32_16x16x32_bf16 v[72:75], v[168:171], v[216:219], v[72:75]
	s_setprio 0
	s_setprio 1
	v_mfma_f32_16x16x32_bf16 v[116:119], v[172:175], v[188:191], v[116:119]
	v_mfma_f32_16x16x32_bf16 v[112:115], v[180:183], v[188:191], v[112:115]
	v_mfma_f32_16x16x32_bf16 v[100:103], v[172:175], v[196:199], v[100:103]
	v_mfma_f32_16x16x32_bf16 v[96:99], v[180:183], v[196:199], v[96:99]
	v_mfma_f32_16x16x32_bf16 v[84:87], v[172:175], v[204:207], v[84:87]
	v_mfma_f32_16x16x32_bf16 v[80:83], v[180:183], v[204:207], v[80:83]
	v_mfma_f32_16x16x32_bf16 v[68:71], v[172:175], v[212:215], v[68:71]
	v_mfma_f32_16x16x32_bf16 v[64:67], v[180:183], v[212:215], v[64:67]
	v_mfma_f32_16x16x32_bf16 v[116:119], v[176:179], v[192:195], v[116:119]
	v_mfma_f32_16x16x32_bf16 v[112:115], v[184:187], v[192:195], v[112:115]
	v_mfma_f32_16x16x32_bf16 v[100:103], v[176:179], v[200:203], v[100:103]
	v_mfma_f32_16x16x32_bf16 v[96:99], v[184:187], v[200:203], v[96:99]
	v_mfma_f32_16x16x32_bf16 v[84:87], v[176:179], v[208:211], v[84:87]
	v_mfma_f32_16x16x32_bf16 v[80:83], v[184:187], v[208:211], v[80:83]
	v_mfma_f32_16x16x32_bf16 v[68:71], v[176:179], v[216:219], v[68:71]
	v_mfma_f32_16x16x32_bf16 v[64:67], v[184:187], v[216:219], v[64:67]
	s_setprio 0
	s_barrier
; #define PG8_STAGE(bufoff, gbase, voff) do { _Pragma("unroll") for (int _i = 0; _i < 2; ++_i) \
;         __builtin_amdgcn_global_load_lds((const unsigned*)((const char*)(gbase) + (voff)[_i]), (PG8_LAS unsigned*)(lds + (bufoff) + ldsw + _i * 8192), 16, 0, 0); } while (0)
; #define PG8_LDA(dst, b, h) do { _Pragma("unroll") for (int m = 0; m < 4; ++m) _Pragma("unroll") for (int k = 0; k < 2; ++k) dst[m][k] = *(const PG8_LAS bf16x8*)(lds + PG8_SA(b, h) + aoff + m * 2048 + k * 1024); } while (0)
; #define PG8_MMA(ai, bj, At, Bt) do { __builtin_amdgcn_s_setprio(1); _Pragma("unroll") for (int m = 0; m < 4; ++m) _Pragma("unroll") for (int n = 0; n < 2; ++n) _Pragma("unroll") for (int k = 0; k < 2; ++k) \
;         acc[ai][bj][m][n] = __builtin_amdgcn_mfma_f32_16x16x32_bf16(Bt[n][k], At[m][k], acc[ai][bj][m][n], 0, 0, 0); __builtin_amdgcn_s_setprio(0); } while (0)
; #define PG8_WAIT_V(n) asm volatile("s_waitcnt vmcnt(" #n ")" ::: "memory")
; #define PG8_WAIT_L(n) asm volatile("s_waitcnt lgkmcnt(" #n ")" ::: "memory")
; #define PG8_BAR __builtin_amdgcn_s_barrier()
; #define PG8_SCHED __builtin_amdgcn_sched_barrier(0)
; template <class Epi, class Sched, bool ALIGN_EPI = false, bool SP2 = false>
; __device__ __forceinline__ void gemm_phase(PG8_LAS unsigned char* lds, const Gemm g, const Sched& S, const Epi& E, int tid_in) {
;     ...
;             PG8_WAIT_V(8); PG8_WAIT_L(0); PG8_BAR; PG8_MMA(0, 0, At, B0); PG8_MMA(0, 1, At, B1); PG8_BAR; PG8_SCHED;
;             PG8_LDA(At, 1, 1); PG8_STAGE(PG8_SB(1, 0), b3, voffB); PG8_STAGE(PG8_SB(1, 1), b3 + hstepB, voffB); PG8_STAGE(PG8_SA(1, 0), a3, voffA);
;             PG8_WAIT_V(8); PG8_WAIT_L(0); PG8_BAR; PG8_MMA(1, 0, At, B0); PG8_MMA(1, 1, At, B1); PG8_BAR; PG8_SCHED;
;     ...
;         if constexpr (ALIGN_EPI) { if (wr == 0) PG8_BAR; }
	s_add_i32 s26, s33, s56
	v_lshl_add_u64 v[220:221], v[220:221], 0, s[12:13]
	s_mov_b32 m0, s26
	ds_read_b128 v[188:191], v152 offset:49152
	ds_read_b128 v[192:195], v152 offset:50176
	ds_read_b128 v[196:199], v152 offset:51200
	ds_read_b128 v[200:203], v152 offset:52224
	ds_read_b128 v[204:207], v152 offset:53248
	ds_read_b128 v[208:211], v152 offset:54272
	ds_read_b128 v[212:215], v152 offset:55296
	ds_read_b128 v[216:219], v152 offset:56320
	global_load_lds_dwordx4 v[220:221], off
	s_add_i32 m0, s26, 0x2000
	s_add_u32 s26, s52, 0x20080
	v_lshl_add_u64 v[220:221], v[222:223], 0, s[12:13]
	s_addc_u32 s27, s53, 0
	s_add_i32 s33, s73, s56
	global_load_lds_dwordx4 v[220:221], off
	v_lshl_add_u64 v[220:221], s[26:27], 0, v[130:131]
	s_mov_b32 m0, s33
	s_nop 0
	global_load_lds_dwordx4 v[220:221], off
	v_lshl_add_u64 v[220:221], s[26:27], 0, v[134:135]
	s_add_i32 m0, s33, 0x2000
	s_nop 0
	global_load_lds_dwordx4 v[220:221], off
	v_lshl_add_u64 v[220:221], v[224:225], 0, s[12:13]
	s_mov_b32 m0, s62
	s_nop 0
	global_load_lds_dwordx4 v[220:221], off
	v_lshl_add_u64 v[220:221], v[226:227], 0, s[12:13]
	s_mov_b32 m0, s63
	s_nop 0
	global_load_lds_dwordx4 v[220:221], off
	s_waitcnt vmcnt(8)
	s_waitcnt lgkmcnt(0)
	s_barrier
	s_setprio 1
	s_waitcnt lgkmcnt(0)
	v_mfma_f32_16x16x32_bf16 v[60:63], v[156:159], v[188:191], v[60:63]
	v_mfma_f32_16x16x32_bf16 v[56:59], v[164:167], v[188:191], v[56:59]
	v_mfma_f32_16x16x32_bf16 v[44:47], v[156:159], v[196:199], v[44:47]
	v_mfma_f32_16x16x32_bf16 v[40:43], v[164:167], v[196:199], v[40:43]
	v_mfma_f32_16x16x32_bf16 v[28:31], v[156:159], v[204:207], v[28:31]
	v_mfma_f32_16x16x32_bf16 v[24:27], v[164:167], v[204:207], v[24:27]
	v_mfma_f32_16x16x32_bf16 v[12:15], v[156:159], v[212:215], v[12:15]
	v_mfma_f32_16x16x32_bf16 v[8:11], v[164:167], v[212:215], v[8:11]
	v_mfma_f32_16x16x32_bf16 v[60:63], v[160:163], v[192:195], v[60:63]
	v_mfma_f32_16x16x32_bf16 v[56:59], v[168:171], v[192:195], v[56:59]
	v_mfma_f32_16x16x32_bf16 v[44:47], v[160:163], v[200:203], v[44:47]
	v_mfma_f32_16x16x32_bf16 v[40:43], v[168:171], v[200:203], v[40:43]
	v_mfma_f32_16x16x32_bf16 v[28:31], v[160:163], v[208:211], v[28:31]
	v_mfma_f32_16x16x32_bf16 v[24:27], v[168:171], v[208:211], v[24:27]
	v_mfma_f32_16x16x32_bf16 v[12:15], v[160:163], v[216:219], v[12:15]
	v_mfma_f32_16x16x32_bf16 v[8:11], v[168:171], v[216:219], v[8:11]
	s_setprio 0
	s_setprio 1
	v_mfma_f32_16x16x32_bf16 v[52:55], v[172:175], v[188:191], v[52:55]
	v_mfma_f32_16x16x32_bf16 v[48:51], v[180:183], v[188:191], v[48:51]
	v_mfma_f32_16x16x32_bf16 v[36:39], v[172:175], v[196:199], v[36:39]
	v_mfma_f32_16x16x32_bf16 v[32:35], v[180:183], v[196:199], v[32:35]
	v_mfma_f32_16x16x32_bf16 v[20:23], v[172:175], v[204:207], v[20:23]
	v_mfma_f32_16x16x32_bf16 v[16:19], v[180:183], v[204:207], v[16:19]
	v_mfma_f32_16x16x32_bf16 v[4:7], v[172:175], v[212:215], v[4:7]
	v_mfma_f32_16x16x32_bf16 v[0:3], v[180:183], v[212:215], v[0:3]
	v_mfma_f32_16x16x32_bf16 v[52:55], v[176:179], v[192:195], v[52:55]
	v_mfma_f32_16x16x32_bf16 v[48:51], v[184:187], v[192:195], v[48:51]
	v_mfma_f32_16x16x32_bf16 v[36:39], v[176:179], v[200:203], v[36:39]
	v_mfma_f32_16x16x32_bf16 v[32:35], v[184:187], v[200:203], v[32:35]
	v_mfma_f32_16x16x32_bf16 v[20:23], v[176:179], v[208:211], v[20:23]
	v_mfma_f32_16x16x32_bf16 v[16:19], v[184:187], v[208:211], v[16:19]
	v_mfma_f32_16x16x32_bf16 v[4:7], v[176:179], v[216:219], v[4:7]
	v_mfma_f32_16x16x32_bf16 v[0:3], v[184:187], v[216:219], v[0:3]
	s_setprio 0
	s_barrier
	s_add_i32 s72, s72, 2
	s_add_u32 s50, s50, 0x100
	s_addc_u32 s51, s51, 0
	s_add_u32 s70, s70, 0x100
	s_addc_u32 s71, s71, 0
	s_cmp_gt_u32 s72, 29
	s_cbranch_scc0 .LBB0_869
	s_add_i32 s99, s99, 1
	s_cmp_lt_u32 s99, 5
	s_cbranch_scc1 .Lapf_skip_6
	s_cmp_gt_u32 s99, 8
	s_cbranch_scc1 .Lapf_skip_6
	s_and_b32 s100, s2, 7
	s_lshl_b32 s100, s100, 24
	s_lshr_b32 s101, s2, 3
	s_lshl_b32 s101, s101, 18
	s_add_i32 s100, s100, s101
	s_lshl_b32 s101, s81, 9
	s_add_i32 s100, s100, s101
	s_sub_i32 s101, s99, 5
	s_lshl_b32 s101, s101, 13
	s_add_i32 s100, s100, s101
	s_add_i32 s100, s100, 0x9000000
	v_lshlrev_b32_e32 v247, 4, v252
	v_add_u32_e32 v247, s100, v247
	global_load_dwordx4 v[248:251], v247, s[18:19]
	global_load_dwordx4 v[248:251], v247, s[18:19] offset:1024
	global_load_dwordx4 v[248:251], v247, s[18:19] offset:2048
	global_load_dwordx4 v[248:251], v247, s[18:19] offset:3072
	v_add_u32_e32 v247, 0x1000, v247
	global_load_dwordx4 v[248:251], v247, s[18:19]
	global_load_dwordx4 v[248:251], v247, s[18:19] offset:1024
	global_load_dwordx4 v[248:251], v247, s[18:19] offset:2048
	global_load_dwordx4 v[248:251], v247, s[18:19] offset:3072
.Lapf_skip_6:
	s_and_b64 vcc, exec, s[36:37]
	s_cbranch_vccz .LBB0_872
	s_barrier
